# P0 rmsnorm row pass rewritten with the next row prefetched
# speedup vs baseline: 1.0574x; 1.0066x over previous
; __device__ __forceinline__ void rms_row_to_bf16(const float* xrow, const float* w, bf16_t* orow, int lane) {
;     f32x4 v[8], ww[8]; float s = 0.f;
; #pragma unroll
;     for (int j = 0; j < 8; ++j) { v[j] = *(const f32x4*)(xrow + (j * 64 + lane) * 4); ww[j] = *(const f32x4*)(w + (j * 64 + lane) * 4); }
; #pragma unroll
;     for (int j = 0; j < 8; ++j) s += (v[j].x * v[j].x + v[j].y * v[j].y) + (v[j].z * v[j].z + v[j].w * v[j].w);
;     const float r = rsqrtf(wave_sum(s) * (1.f / DM) + EPS);
; __global__ void __launch_bounds__(512, 2) mk_fwd(Args args) {
;     ...
;         const int gr = (gw + NGW - (n_items0 % NGW)) % NGW;
;         for (int m = gr; m < MT; m += NGW) { const float* xr = (m < MP) ? x_prompt + (size_t)m * DM : x_sample + (size_t)(m - MP) * DM; rms_row_to_bf16(xr, norm_mix_w, XN + (size_t)m * DM, lane); }
.LBB0_54:
	s_abs_i32 s4, s10
	v_cvt_f32_u32_e32 v1, s4
	s_sub_i32 s5, 0, s4
	s_add_i32 s3, s3, s10
	v_rcp_iflag_f32_e32 v1, v1
	s_nop 0
	v_mul_f32_e32 v1, 0x4f7ffffe, v1
	v_cvt_u32_f32_e32 v1, v1
	s_nop 0
	v_readfirstlane_b32 s6, v1
	s_mul_i32 s5, s5, s6
	s_mul_hi_u32 s5, s6, s5
	s_add_i32 s6, s6, s5
	s_mul_hi_u32 s5, s6, 0x4430
	s_mul_i32 s5, s5, s4
	s_sub_i32 s5, 0x4430, s5
	s_sub_i32 s7, s5, s4
	s_cmp_ge_u32 s5, s4
	s_cselect_b32 s5, s7, s5
	s_sub_i32 s7, s5, s4
	s_cmp_ge_u32 s5, s4
	s_cselect_b32 s5, s7, s5
	s_sub_i32 s3, s3, s5
	s_ashr_i32 s5, s3, 31
	s_abs_i32 s3, s3
	s_mul_hi_u32 s6, s3, s6
	s_mul_i32 s6, s6, s4
	s_sub_i32 s3, s3, s6
	s_sub_i32 s6, s3, s4
	s_cmp_ge_u32 s3, s4
	s_cselect_b32 s3, s6, s3
	s_sub_i32 s6, s3, s4
	s_cmp_ge_u32 s3, s4
	s_cselect_b32 s3, s6, s3
	s_xor_b32 s3, s3, s5
	s_sub_i32 s4, s3, s5
	s_cmpk_gt_i32 s4, 0x21ff
	s_mov_b32 s7, 0
	s_cbranch_scc1 .LBB0_61
	s_load_dwordx2 s[12:13], s[8:9], 0x0
	s_load_dwordx2 s[14:15], s[8:9], 0x8
	s_load_dwordx2 s[16:17], s[8:9], 0x30
	s_load_dwordx2 s[18:19], s[8:9], 0xd0
	v_lshlrev_b32_e32 v4, 4, v3
	v_lshlrev_b32_e32 v5, 3, v3
	v_xor_b32_e32 v6, 1, v3
	v_lshlrev_b32_e32 v6, 2, v6
	v_xor_b32_e32 v7, 2, v3
	v_lshlrev_b32_e32 v7, 2, v7
	v_xor_b32_e32 v8, 4, v3
	v_lshlrev_b32_e32 v8, 2, v8
	v_xor_b32_e32 v9, 8, v3
	v_lshlrev_b32_e32 v9, 2, v9
	v_xor_b32_e32 v10, 16, v3
	v_lshlrev_b32_e32 v10, 2, v10
	v_xor_b32_e32 v11, 32, v3
	v_lshlrev_b32_e32 v11, 2, v11
	v_mov_b32_e32 v16, 0x3727c5ac
	s_waitcnt lgkmcnt(0)
	s_add_u32 s18, s18, 0x7580000
	s_addc_u32 s19, s19, 0
	global_load_dwordx4 v[40:43], v4, s[16:17] offset:0
	global_load_dwordx4 v[44:47], v4, s[16:17] offset:1024
	global_load_dwordx4 v[48:51], v4, s[16:17] offset:2048
	global_load_dwordx4 v[52:55], v4, s[16:17] offset:3072
	s_add_u32 s16, s16, 4096
	s_addc_u32 s17, s17, 0
	global_load_dwordx4 v[56:59], v4, s[16:17] offset:0
	global_load_dwordx4 v[60:63], v4, s[16:17] offset:1024
	global_load_dwordx4 v[64:67], v4, s[16:17] offset:2048
	global_load_dwordx4 v[68:71], v4, s[16:17] offset:3072
	s_cmpk_lt_u32 s4, 8192
	s_cselect_b32 s20, s12, s14
	s_cselect_b32 s21, s13, s15
	s_cselect_b32 s28, 0, 8192
	s_sub_u32 s28, s4, s28
	s_lshr_b32 s29, s28, 19
	s_lshl_b32 s28, s28, 13
	s_add_u32 s20, s20, s28
	s_addc_u32 s21, s21, s29
	global_load_dwordx4 v[72:75], v4, s[20:21] offset:0 nt
	global_load_dwordx4 v[76:79], v4, s[20:21] offset:1024 nt
	global_load_dwordx4 v[80:83], v4, s[20:21] offset:2048 nt
	global_load_dwordx4 v[84:87], v4, s[20:21] offset:3072 nt
	s_add_u32 s20, s20, 4096
	s_addc_u32 s21, s21, 0
	global_load_dwordx4 v[88:91], v4, s[20:21] offset:0 nt
	global_load_dwordx4 v[92:95], v4, s[20:21] offset:1024 nt
	global_load_dwordx4 v[96:99], v4, s[20:21] offset:2048 nt
	global_load_dwordx4 v[100:103], v4, s[20:21] offset:3072 nt
	s_mov_b32 s27, 0
.Lrows_a:
	s_add_u32 s25, s4, s10
	s_mov_b32 s24, s27
	s_cmpk_lt_u32 s25, 8704
	s_cbranch_scc0 .Lrows_nonext_a
	s_cmpk_lt_u32 s25, 8192
	s_cselect_b32 s20, s12, s14
	s_cselect_b32 s21, s13, s15
	s_cselect_b32 s28, 0, 8192
	s_sub_u32 s28, s25, s28
	s_lshr_b32 s29, s28, 19
	s_lshl_b32 s28, s28, 13
	s_add_u32 s20, s20, s28
	s_addc_u32 s21, s21, s29
	global_load_dwordx4 v[104:107], v4, s[20:21] offset:0 nt
	global_load_dwordx4 v[108:111], v4, s[20:21] offset:1024 nt
	global_load_dwordx4 v[112:115], v4, s[20:21] offset:2048 nt
	global_load_dwordx4 v[116:119], v4, s[20:21] offset:3072 nt
	s_add_u32 s20, s20, 4096
	s_addc_u32 s21, s21, 0
	global_load_dwordx4 v[120:123], v4, s[20:21] offset:0 nt
	global_load_dwordx4 v[124:127], v4, s[20:21] offset:1024 nt
	global_load_dwordx4 v[128:131], v4, s[20:21] offset:2048 nt
	global_load_dwordx4 v[132:135], v4, s[20:21] offset:3072 nt
	s_add_u32 s24, s24, 1
.Lrows_nonext_a:
	s_cmp_eq_u32 s24, 2
	s_cbranch_scc1 .Lrows_w16_a
	s_cmp_eq_u32 s24, 1
	s_cbranch_scc1 .Lrows_w8_a
	s_waitcnt vmcnt(0)
	s_branch .Lrows_wd_a
.Lrows_w16_a:
	s_waitcnt vmcnt(16)
	s_branch .Lrows_wd_a
.Lrows_w8_a:
	s_waitcnt vmcnt(8)
; __device__ __forceinline__ unsigned pk2(float lo, float hi) { unsigned r; asm("v_cvt_pk_bf16_f32 %0, %1, %2" : "=v"(r) : "v"(lo), "v"(hi)); return r; }
; __device__ __forceinline__ void rms_row_to_bf16(const float* xrow, const float* w, bf16_t* orow, int lane) {
;     ...
;     for (int j = 0; j < 8; ++j) { v[j] = *(const f32x4*)(xrow + (j * 64 + lane) * 4); ww[j] = *(const f32x4*)(w + (j * 64 + lane) * 4); }
; #pragma unroll
;     for (int j = 0; j < 8; ++j) s += (v[j].x * v[j].x + v[j].y * v[j].y) + (v[j].z * v[j].z + v[j].w * v[j].w);
;     const float r = rsqrtf(wave_sum(s) * (1.f / DM) + EPS);
; #pragma unroll
;     for (int j = 0; j < 8; ++j) {
;         u32x2 o; o.x = pk2(v[j].x * r * ww[j].x, v[j].y * r * ww[j].y); o.y = pk2(v[j].z * r * ww[j].z, v[j].w * r * ww[j].w);
;         *(u32x2*)(orow + (j * 64 + lane) * 4) = o; }
.Lrows_wd_a:
	v_mov_b32_e32 v12, 0
	v_mul_f32_e32 v13, v72, v72
	v_mul_f32_e32 v14, v74, v74
	v_fmac_f32_e32 v13, v73, v73
	v_fmac_f32_e32 v14, v75, v75
	v_add_f32_e32 v13, v13, v14
	v_add_f32_e32 v12, v12, v13
	v_mul_f32_e32 v13, v76, v76
	v_mul_f32_e32 v14, v78, v78
	v_fmac_f32_e32 v13, v77, v77
	v_fmac_f32_e32 v14, v79, v79
	v_add_f32_e32 v13, v13, v14
	v_add_f32_e32 v12, v12, v13
	v_mul_f32_e32 v13, v80, v80
	v_mul_f32_e32 v14, v82, v82
	v_fmac_f32_e32 v13, v81, v81
	v_fmac_f32_e32 v14, v83, v83
	v_add_f32_e32 v13, v13, v14
	v_add_f32_e32 v12, v12, v13
	v_mul_f32_e32 v13, v84, v84
	v_mul_f32_e32 v14, v86, v86
	v_fmac_f32_e32 v13, v85, v85
	v_fmac_f32_e32 v14, v87, v87
	v_add_f32_e32 v13, v13, v14
	v_add_f32_e32 v12, v12, v13
	v_mul_f32_e32 v13, v88, v88
	v_mul_f32_e32 v14, v90, v90
	v_fmac_f32_e32 v13, v89, v89
	v_fmac_f32_e32 v14, v91, v91
	v_add_f32_e32 v13, v13, v14
	v_add_f32_e32 v12, v12, v13
	v_mul_f32_e32 v13, v92, v92
	v_mul_f32_e32 v14, v94, v94
	v_fmac_f32_e32 v13, v93, v93
	v_fmac_f32_e32 v14, v95, v95
	v_add_f32_e32 v13, v13, v14
	v_add_f32_e32 v12, v12, v13
	v_mul_f32_e32 v13, v96, v96
	v_mul_f32_e32 v14, v98, v98
	v_fmac_f32_e32 v13, v97, v97
	v_fmac_f32_e32 v14, v99, v99
	v_add_f32_e32 v13, v13, v14
	v_add_f32_e32 v12, v12, v13
	v_mul_f32_e32 v13, v100, v100
	v_mul_f32_e32 v14, v102, v102
	v_fmac_f32_e32 v13, v101, v101
	v_fmac_f32_e32 v14, v103, v103
	v_add_f32_e32 v13, v13, v14
	v_add_f32_e32 v12, v12, v13
	ds_bpermute_b32 v13, v6, v12
	s_waitcnt lgkmcnt(0)
	v_add_f32_e32 v12, v12, v13
	ds_bpermute_b32 v13, v7, v12
	s_waitcnt lgkmcnt(0)
	v_add_f32_e32 v12, v12, v13
	ds_bpermute_b32 v13, v8, v12
	s_waitcnt lgkmcnt(0)
	v_add_f32_e32 v12, v12, v13
	ds_bpermute_b32 v13, v9, v12
	s_waitcnt lgkmcnt(0)
	v_add_f32_e32 v12, v12, v13
	ds_bpermute_b32 v13, v10, v12
	s_waitcnt lgkmcnt(0)
	v_add_f32_e32 v12, v12, v13
	ds_bpermute_b32 v13, v11, v12
	s_waitcnt lgkmcnt(0)
	v_add_f32_e32 v12, v12, v13
	v_fmamk_f32 v12, v12, 0x3a000000, v16
	v_rsq_f32_e32 v15, v12
	s_lshr_b32 s23, s4, 20
	s_lshl_b32 s22, s4, 12
	s_add_u32 s22, s22, s18
	s_addc_u32 s23, s23, s19
	v_mul_f32_e32 v72, v72, v15
	v_mul_f32_e32 v73, v73, v15
	v_mul_f32_e32 v74, v74, v15
	v_mul_f32_e32 v75, v75, v15
	v_mul_f32_e32 v72, v72, v40
	v_mul_f32_e32 v73, v73, v41
	v_mul_f32_e32 v74, v74, v42
	v_mul_f32_e32 v75, v75, v43
	v_cvt_pk_bf16_f32 v18, v72, v73
	v_cvt_pk_bf16_f32 v19, v74, v75
	global_store_dwordx2 v5, v[18:19], s[22:23] offset:0
	v_mul_f32_e32 v76, v76, v15
	v_mul_f32_e32 v77, v77, v15
	v_mul_f32_e32 v78, v78, v15
	v_mul_f32_e32 v79, v79, v15
	v_mul_f32_e32 v76, v76, v44
	v_mul_f32_e32 v77, v77, v45
	v_mul_f32_e32 v78, v78, v46
	v_mul_f32_e32 v79, v79, v47
	v_cvt_pk_bf16_f32 v20, v76, v77
	v_cvt_pk_bf16_f32 v21, v78, v79
	global_store_dwordx2 v5, v[20:21], s[22:23] offset:512
	v_mul_f32_e32 v80, v80, v15
	v_mul_f32_e32 v81, v81, v15
	v_mul_f32_e32 v82, v82, v15
	v_mul_f32_e32 v83, v83, v15
	v_mul_f32_e32 v80, v80, v48
	v_mul_f32_e32 v81, v81, v49
	v_mul_f32_e32 v82, v82, v50
	v_mul_f32_e32 v83, v83, v51
	v_cvt_pk_bf16_f32 v22, v80, v81
	v_cvt_pk_bf16_f32 v23, v82, v83
	global_store_dwordx2 v5, v[22:23], s[22:23] offset:1024
	v_mul_f32_e32 v84, v84, v15
	v_mul_f32_e32 v85, v85, v15
	v_mul_f32_e32 v86, v86, v15
	v_mul_f32_e32 v87, v87, v15
	v_mul_f32_e32 v84, v84, v52
	v_mul_f32_e32 v85, v85, v53
	v_mul_f32_e32 v86, v86, v54
	v_mul_f32_e32 v87, v87, v55
	v_cvt_pk_bf16_f32 v24, v84, v85
	v_cvt_pk_bf16_f32 v25, v86, v87
	global_store_dwordx2 v5, v[24:25], s[22:23] offset:1536
	v_mul_f32_e32 v88, v88, v15
	v_mul_f32_e32 v89, v89, v15
	v_mul_f32_e32 v90, v90, v15
	v_mul_f32_e32 v91, v91, v15
	v_mul_f32_e32 v88, v88, v56
	v_mul_f32_e32 v89, v89, v57
	v_mul_f32_e32 v90, v90, v58
	v_mul_f32_e32 v91, v91, v59
	v_cvt_pk_bf16_f32 v26, v88, v89
	v_cvt_pk_bf16_f32 v27, v90, v91
	global_store_dwordx2 v5, v[26:27], s[22:23] offset:2048
	v_mul_f32_e32 v92, v92, v15
	v_mul_f32_e32 v93, v93, v15
	v_mul_f32_e32 v94, v94, v15
	v_mul_f32_e32 v95, v95, v15
	v_mul_f32_e32 v92, v92, v60
	v_mul_f32_e32 v93, v93, v61
	v_mul_f32_e32 v94, v94, v62
	v_mul_f32_e32 v95, v95, v63
	v_cvt_pk_bf16_f32 v28, v92, v93
	v_cvt_pk_bf16_f32 v29, v94, v95
	global_store_dwordx2 v5, v[28:29], s[22:23] offset:2560
	v_mul_f32_e32 v96, v96, v15
	v_mul_f32_e32 v97, v97, v15
	v_mul_f32_e32 v98, v98, v15
	v_mul_f32_e32 v99, v99, v15
	v_mul_f32_e32 v96, v96, v64
	v_mul_f32_e32 v97, v97, v65
	v_mul_f32_e32 v98, v98, v66
	v_mul_f32_e32 v99, v99, v67
	v_cvt_pk_bf16_f32 v30, v96, v97
	v_cvt_pk_bf16_f32 v31, v98, v99
	global_store_dwordx2 v5, v[30:31], s[22:23] offset:3072
	v_mul_f32_e32 v100, v100, v15
	v_mul_f32_e32 v101, v101, v15
	v_mul_f32_e32 v102, v102, v15
	v_mul_f32_e32 v103, v103, v15
	v_mul_f32_e32 v100, v100, v68
	v_mul_f32_e32 v101, v101, v69
	v_mul_f32_e32 v102, v102, v70
	v_mul_f32_e32 v103, v103, v71
	v_cvt_pk_bf16_f32 v32, v100, v101
	v_cvt_pk_bf16_f32 v33, v102, v103
	global_store_dwordx2 v5, v[32:33], s[22:23] offset:3584
	s_mov_b32 s27, 1
	s_mov_b32 s4, s25
	s_cmpk_lt_u32 s4, 8704
	s_cbranch_scc1 .Lrows_b
	s_branch .Lrows_done
.Lrows_b:
	s_add_u32 s25, s4, s10
	s_mov_b32 s24, s27
	s_cmpk_lt_u32 s25, 8704
	s_cbranch_scc0 .Lrows_nonext_b
	s_cmpk_lt_u32 s25, 8192
	s_cselect_b32 s20, s12, s14
	s_cselect_b32 s21, s13, s15
	s_cselect_b32 s28, 0, 8192
	s_sub_u32 s28, s25, s28
	s_lshr_b32 s29, s28, 19
	s_lshl_b32 s28, s28, 13
	s_add_u32 s20, s20, s28
	s_addc_u32 s21, s21, s29
	global_load_dwordx4 v[72:75], v4, s[20:21] offset:0 nt
	global_load_dwordx4 v[76:79], v4, s[20:21] offset:1024 nt
	global_load_dwordx4 v[80:83], v4, s[20:21] offset:2048 nt
	global_load_dwordx4 v[84:87], v4, s[20:21] offset:3072 nt
	s_add_u32 s20, s20, 4096
	s_addc_u32 s21, s21, 0
	global_load_dwordx4 v[88:91], v4, s[20:21] offset:0 nt
	global_load_dwordx4 v[92:95], v4, s[20:21] offset:1024 nt
	global_load_dwordx4 v[96:99], v4, s[20:21] offset:2048 nt
	global_load_dwordx4 v[100:103], v4, s[20:21] offset:3072 nt
	s_add_u32 s24, s24, 1

; __device__ __forceinline__ unsigned pk2(float lo, float hi) { unsigned r; asm("v_cvt_pk_bf16_f32 %0, %1, %2" : "=v"(r) : "v"(lo), "v"(hi)); return r; }
; __device__ __forceinline__ void rms_row_to_bf16(const float* xrow, const float* w, bf16_t* orow, int lane) {
;     ...
;     for (int j = 0; j < 8; ++j) { v[j] = *(const f32x4*)(xrow + (j * 64 + lane) * 4); ww[j] = *(const f32x4*)(w + (j * 64 + lane) * 4); }
; #pragma unroll
;     for (int j = 0; j < 8; ++j) s += (v[j].x * v[j].x + v[j].y * v[j].y) + (v[j].z * v[j].z + v[j].w * v[j].w);
;     const float r = rsqrtf(wave_sum(s) * (1.f / DM) + EPS);
; #pragma unroll
;     for (int j = 0; j < 8; ++j) {
;         u32x2 o; o.x = pk2(v[j].x * r * ww[j].x, v[j].y * r * ww[j].y); o.y = pk2(v[j].z * r * ww[j].z, v[j].w * r * ww[j].w);
;         *(u32x2*)(orow + (j * 64 + lane) * 4) = o; }
; __device__ __forceinline__ void xcd_barrier(const XcdBarrier& b) {
;     asm volatile("s_waitcnt vmcnt(0)" ::: "memory");
;     __syncthreads();
;     if (threadIdx.x == 0) {
;         unsigned* bar = b.bar;
;         __builtin_amdgcn_s_waitcnt(0);
;         unsigned nloc = b.st[0], nx = b.st[1];
;         if (nloc == 0u) { xcd_barrier_complete(bar, b.x, nloc, nx); b.st[0] = nloc; b.st[1] = nx; }
.Lrows_wd_b:
	v_mov_b32_e32 v12, 0
	v_mul_f32_e32 v13, v104, v104
	v_mul_f32_e32 v14, v106, v106
	v_fmac_f32_e32 v13, v105, v105
	v_fmac_f32_e32 v14, v107, v107
	v_add_f32_e32 v13, v13, v14
	v_add_f32_e32 v12, v12, v13
	v_mul_f32_e32 v13, v108, v108
	v_mul_f32_e32 v14, v110, v110
	v_fmac_f32_e32 v13, v109, v109
	v_fmac_f32_e32 v14, v111, v111
	v_add_f32_e32 v13, v13, v14
	v_add_f32_e32 v12, v12, v13
	v_mul_f32_e32 v13, v112, v112
	v_mul_f32_e32 v14, v114, v114
	v_fmac_f32_e32 v13, v113, v113
	v_fmac_f32_e32 v14, v115, v115
	v_add_f32_e32 v13, v13, v14
	v_add_f32_e32 v12, v12, v13
	v_mul_f32_e32 v13, v116, v116
	v_mul_f32_e32 v14, v118, v118
	v_fmac_f32_e32 v13, v117, v117
	v_fmac_f32_e32 v14, v119, v119
	v_add_f32_e32 v13, v13, v14
	v_add_f32_e32 v12, v12, v13
	v_mul_f32_e32 v13, v120, v120
	v_mul_f32_e32 v14, v122, v122
	v_fmac_f32_e32 v13, v121, v121
	v_fmac_f32_e32 v14, v123, v123
	v_add_f32_e32 v13, v13, v14
	v_add_f32_e32 v12, v12, v13
	v_mul_f32_e32 v13, v124, v124
	v_mul_f32_e32 v14, v126, v126
	v_fmac_f32_e32 v13, v125, v125
	v_fmac_f32_e32 v14, v127, v127
	v_add_f32_e32 v13, v13, v14
	v_add_f32_e32 v12, v12, v13
	v_mul_f32_e32 v13, v128, v128
	v_mul_f32_e32 v14, v130, v130
	v_fmac_f32_e32 v13, v129, v129
	v_fmac_f32_e32 v14, v131, v131
	v_add_f32_e32 v13, v13, v14
	v_add_f32_e32 v12, v12, v13
	v_mul_f32_e32 v13, v132, v132
	v_mul_f32_e32 v14, v134, v134
	v_fmac_f32_e32 v13, v133, v133
	v_fmac_f32_e32 v14, v135, v135
	v_add_f32_e32 v13, v13, v14
	v_add_f32_e32 v12, v12, v13
	ds_bpermute_b32 v13, v6, v12
	s_waitcnt lgkmcnt(0)
	v_add_f32_e32 v12, v12, v13
	ds_bpermute_b32 v13, v7, v12
	s_waitcnt lgkmcnt(0)
	v_add_f32_e32 v12, v12, v13
	ds_bpermute_b32 v13, v8, v12
	s_waitcnt lgkmcnt(0)
	v_add_f32_e32 v12, v12, v13
	ds_bpermute_b32 v13, v9, v12
	s_waitcnt lgkmcnt(0)
	v_add_f32_e32 v12, v12, v13
	ds_bpermute_b32 v13, v10, v12
	s_waitcnt lgkmcnt(0)
	v_add_f32_e32 v12, v12, v13
	ds_bpermute_b32 v13, v11, v12
	s_waitcnt lgkmcnt(0)
	v_add_f32_e32 v12, v12, v13
	v_fmamk_f32 v12, v12, 0x3a000000, v16
	v_rsq_f32_e32 v15, v12
	s_lshr_b32 s23, s4, 20
	s_lshl_b32 s22, s4, 12
	s_add_u32 s22, s22, s18
	s_addc_u32 s23, s23, s19
	v_mul_f32_e32 v104, v104, v15
	v_mul_f32_e32 v105, v105, v15
	v_mul_f32_e32 v106, v106, v15
	v_mul_f32_e32 v107, v107, v15
	v_mul_f32_e32 v104, v104, v40
	v_mul_f32_e32 v105, v105, v41
	v_mul_f32_e32 v106, v106, v42
	v_mul_f32_e32 v107, v107, v43
	v_cvt_pk_bf16_f32 v18, v104, v105
	v_cvt_pk_bf16_f32 v19, v106, v107
	global_store_dwordx2 v5, v[18:19], s[22:23] offset:0
	v_mul_f32_e32 v108, v108, v15
	v_mul_f32_e32 v109, v109, v15
	v_mul_f32_e32 v110, v110, v15
	v_mul_f32_e32 v111, v111, v15
	v_mul_f32_e32 v108, v108, v44
	v_mul_f32_e32 v109, v109, v45
	v_mul_f32_e32 v110, v110, v46
	v_mul_f32_e32 v111, v111, v47
	v_cvt_pk_bf16_f32 v20, v108, v109
	v_cvt_pk_bf16_f32 v21, v110, v111
	global_store_dwordx2 v5, v[20:21], s[22:23] offset:512
	v_mul_f32_e32 v112, v112, v15
	v_mul_f32_e32 v113, v113, v15
	v_mul_f32_e32 v114, v114, v15
	v_mul_f32_e32 v115, v115, v15
	v_mul_f32_e32 v112, v112, v48
	v_mul_f32_e32 v113, v113, v49
	v_mul_f32_e32 v114, v114, v50
	v_mul_f32_e32 v115, v115, v51
	v_cvt_pk_bf16_f32 v22, v112, v113
	v_cvt_pk_bf16_f32 v23, v114, v115
	global_store_dwordx2 v5, v[22:23], s[22:23] offset:1024
	v_mul_f32_e32 v116, v116, v15
	v_mul_f32_e32 v117, v117, v15
	v_mul_f32_e32 v118, v118, v15
	v_mul_f32_e32 v119, v119, v15
	v_mul_f32_e32 v116, v116, v52
	v_mul_f32_e32 v117, v117, v53
	v_mul_f32_e32 v118, v118, v54
	v_mul_f32_e32 v119, v119, v55
	v_cvt_pk_bf16_f32 v24, v116, v117
	v_cvt_pk_bf16_f32 v25, v118, v119
	global_store_dwordx2 v5, v[24:25], s[22:23] offset:1536
	v_mul_f32_e32 v120, v120, v15
	v_mul_f32_e32 v121, v121, v15
	v_mul_f32_e32 v122, v122, v15
	v_mul_f32_e32 v123, v123, v15
	v_mul_f32_e32 v120, v120, v56
	v_mul_f32_e32 v121, v121, v57
	v_mul_f32_e32 v122, v122, v58
	v_mul_f32_e32 v123, v123, v59
	v_cvt_pk_bf16_f32 v26, v120, v121
	v_cvt_pk_bf16_f32 v27, v122, v123
	global_store_dwordx2 v5, v[26:27], s[22:23] offset:2048
	v_mul_f32_e32 v124, v124, v15
	v_mul_f32_e32 v125, v125, v15
	v_mul_f32_e32 v126, v126, v15
	v_mul_f32_e32 v127, v127, v15
	v_mul_f32_e32 v124, v124, v60
	v_mul_f32_e32 v125, v125, v61
	v_mul_f32_e32 v126, v126, v62
	v_mul_f32_e32 v127, v127, v63
	v_cvt_pk_bf16_f32 v28, v124, v125
	v_cvt_pk_bf16_f32 v29, v126, v127
	global_store_dwordx2 v5, v[28:29], s[22:23] offset:2560
	v_mul_f32_e32 v128, v128, v15
	v_mul_f32_e32 v129, v129, v15
	v_mul_f32_e32 v130, v130, v15
	v_mul_f32_e32 v131, v131, v15
	v_mul_f32_e32 v128, v128, v64
	v_mul_f32_e32 v129, v129, v65
	v_mul_f32_e32 v130, v130, v66
	v_mul_f32_e32 v131, v131, v67
	v_cvt_pk_bf16_f32 v30, v128, v129
	v_cvt_pk_bf16_f32 v31, v130, v131
	global_store_dwordx2 v5, v[30:31], s[22:23] offset:3072
	v_mul_f32_e32 v132, v132, v15
	v_mul_f32_e32 v133, v133, v15
	v_mul_f32_e32 v134, v134, v15
	v_mul_f32_e32 v135, v135, v15
	v_mul_f32_e32 v132, v132, v68
	v_mul_f32_e32 v133, v133, v69
	v_mul_f32_e32 v134, v134, v70
	v_mul_f32_e32 v135, v135, v71
	v_cvt_pk_bf16_f32 v32, v132, v133
	v_cvt_pk_bf16_f32 v33, v134, v135
	global_store_dwordx2 v5, v[32:33], s[22:23] offset:3584
	s_mov_b32 s27, 1
	s_mov_b32 s4, s25
	s_cmpk_lt_u32 s4, 8704
	s_cbranch_scc1 .Lrows_a
	s_branch .Lrows_done
.Lrows_done:
.LBB0_61:
	s_cmp_gt_i32 s89, 1
	s_cselect_b64 s[4:5], -1, 0
	s_and_b64 s[0:1], s[0:1], s[4:5]
	s_andn2_b64 vcc, exec, s[0:1]
	s_cbranch_vccnz .LBB0_116
	s_waitcnt vmcnt(0)
	s_barrier
	s_mov_b64 s[0:1], exec
	v_readlane_b32 s6, v253, 4
	v_readlane_b32 s7, v253, 5
	s_and_b64 s[6:7], s[0:1], s[6:7]
	s_mov_b64 exec, s[6:7]
	s_cbranch_execz .LBB0_115
	s_add_i32 s3, 0, 0x23fc0
	v_mov_b32_e32 v0, s3
	s_waitcnt vmcnt(0) expcnt(0) lgkmcnt(0)
	ds_read_b32 v2, v0
	s_add_i32 s3, 0, 0x23fc4
	v_mov_b32_e32 v0, s3
	ds_read_b32 v0, v0
	s_waitcnt lgkmcnt(1)
	v_cmp_ne_u32_e32 vcc, 0, v2
	s_cbranch_vccnz .LBB0_79
	v_readlane_b32 s6, v253, 0
	v_readlane_b32 s7, v253, 1
	s_load_dwordx2 s[10:11], s[6:7], 0x4
	s_add_u32 s6, s74, 0x1000
	s_addc_u32 s7, s75, 0
	s_add_u32 s8, s74, 0x1100
	s_addc_u32 s9, s75, 0
	s_waitcnt lgkmcnt(0)
	s_mul_i32 s3, s10, s94
	s_add_u32 s10, s74, 0x1200
	s_mul_i32 s3, s3, s11
	s_addc_u32 s11, s75, 0
	s_add_u32 s12, s74, 0x1300
	s_addc_u32 s13, s75, 0
	s_mov_b32 s20, 1
	v_mov_b32_e32 v16, 0
	s_branch .LBB0_66

;     __device__ __forceinline__ void operator()(const f32x4 (&acc)[2][2][4][2], const Unit& u, int wr, int wc, int fr, int fq) const {
;     ...
;         const int col0 = u.pn * BM + wc * 32 + 8 * fq;
;         float rs[2][4];
; #pragma unroll
;         for (int ai = 0; ai < 2; ++ai)
; #pragma unroll
;             for (int m = 0; m < 4; ++m) rs[ai][m] = ssq ? rsqrtf(ssq[row0 + ai * HALF + m * 16] * (1.f / DM) + EPS) : 1.f;
.Lepi7_rs:
	v_fmamk_f32 v158, v158, 0x3a000000, v157
	v_fmamk_f32 v159, v159, 0x3a000000, v157
	v_fmamk_f32 v160, v160, 0x3a000000, v157
	v_fmamk_f32 v161, v161, 0x3a000000, v157
	v_fmamk_f32 v162, v162, 0x3a000000, v157
	v_fmamk_f32 v163, v163, 0x3a000000, v157
	v_fmamk_f32 v164, v164, 0x3a000000, v157
	v_fmamk_f32 v165, v165, 0x3a000000, v157
	v_rsq_f32_e32 v158, v158
	v_rsq_f32_e32 v159, v159
	v_rsq_f32_e32 v160, v160
	v_rsq_f32_e32 v161, v161
	v_rsq_f32_e32 v162, v162
	v_rsq_f32_e32 v163, v163
	v_rsq_f32_e32 v164, v164
	v_rsq_f32_e32 v165, v165
	s_nop 0
	v_mul_f32_e32 v112, v112, v158
	v_mul_f32_e32 v113, v113, v158
	v_mul_f32_e32 v114, v114, v158
	v_mul_f32_e32 v115, v115, v158
	v_mul_f32_e32 v116, v116, v158
	v_mul_f32_e32 v117, v117, v158
	v_mul_f32_e32 v118, v118, v158
	v_mul_f32_e32 v119, v119, v158
	v_mul_f32_e32 v120, v120, v158
	v_mul_f32_e32 v121, v121, v158
	v_mul_f32_e32 v122, v122, v158
	v_mul_f32_e32 v123, v123, v158
	v_mul_f32_e32 v124, v124, v158
	v_mul_f32_e32 v125, v125, v158
	v_mul_f32_e32 v126, v126, v158
	v_mul_f32_e32 v127, v127, v158
	v_mul_f32_e32 v96, v96, v159
	v_mul_f32_e32 v97, v97, v159
	v_mul_f32_e32 v98, v98, v159
	v_mul_f32_e32 v99, v99, v159
	v_mul_f32_e32 v100, v100, v159
	v_mul_f32_e32 v101, v101, v159
	v_mul_f32_e32 v102, v102, v159
	v_mul_f32_e32 v103, v103, v159
	v_mul_f32_e32 v104, v104, v159
	v_mul_f32_e32 v105, v105, v159
	v_mul_f32_e32 v106, v106, v159
	v_mul_f32_e32 v107, v107, v159
	v_mul_f32_e32 v108, v108, v159
	v_mul_f32_e32 v109, v109, v159
	v_mul_f32_e32 v110, v110, v159
	v_mul_f32_e32 v111, v111, v159
	v_mul_f32_e32 v80, v80, v160
	v_mul_f32_e32 v81, v81, v160
	v_mul_f32_e32 v82, v82, v160
	v_mul_f32_e32 v83, v83, v160
	v_mul_f32_e32 v84, v84, v160
	v_mul_f32_e32 v85, v85, v160
	v_mul_f32_e32 v86, v86, v160
	v_mul_f32_e32 v87, v87, v160
	v_mul_f32_e32 v88, v88, v160
	v_mul_f32_e32 v89, v89, v160
	v_mul_f32_e32 v90, v90, v160
	v_mul_f32_e32 v91, v91, v160
	v_mul_f32_e32 v92, v92, v160
	v_mul_f32_e32 v93, v93, v160
	v_mul_f32_e32 v94, v94, v160
	v_mul_f32_e32 v95, v95, v160
	v_mul_f32_e32 v64, v64, v161
	v_mul_f32_e32 v65, v65, v161
	v_mul_f32_e32 v66, v66, v161
	v_mul_f32_e32 v67, v67, v161
	v_mul_f32_e32 v68, v68, v161
	v_mul_f32_e32 v69, v69, v161
	v_mul_f32_e32 v70, v70, v161
	v_mul_f32_e32 v71, v71, v161
	v_mul_f32_e32 v72, v72, v161
	v_mul_f32_e32 v73, v73, v161
	v_mul_f32_e32 v74, v74, v161
	v_mul_f32_e32 v75, v75, v161
	v_mul_f32_e32 v76, v76, v161
	v_mul_f32_e32 v77, v77, v161
	v_mul_f32_e32 v78, v78, v161
	v_mul_f32_e32 v79, v79, v161
	v_mul_f32_e32 v48, v48, v162
	v_mul_f32_e32 v49, v49, v162
	v_mul_f32_e32 v50, v50, v162
	v_mul_f32_e32 v51, v51, v162
	v_mul_f32_e32 v52, v52, v162
	v_mul_f32_e32 v53, v53, v162
	v_mul_f32_e32 v54, v54, v162
	v_mul_f32_e32 v55, v55, v162
	v_mul_f32_e32 v56, v56, v162
	v_mul_f32_e32 v57, v57, v162
	v_mul_f32_e32 v58, v58, v162
	v_mul_f32_e32 v59, v59, v162
	v_mul_f32_e32 v60, v60, v162
	v_mul_f32_e32 v61, v61, v162
	v_mul_f32_e32 v62, v62, v162
	v_mul_f32_e32 v63, v63, v162
	v_mul_f32_e32 v32, v32, v163
	v_mul_f32_e32 v33, v33, v163
	v_mul_f32_e32 v34, v34, v163
	v_mul_f32_e32 v35, v35, v163
	v_mul_f32_e32 v36, v36, v163
	v_mul_f32_e32 v37, v37, v163
	v_mul_f32_e32 v38, v38, v163
	v_mul_f32_e32 v39, v39, v163
	v_mul_f32_e32 v40, v40, v163
	v_mul_f32_e32 v41, v41, v163
	v_mul_f32_e32 v42, v42, v163
	v_mul_f32_e32 v43, v43, v163
	v_mul_f32_e32 v44, v44, v163
	v_mul_f32_e32 v45, v45, v163
	v_mul_f32_e32 v46, v46, v163
	v_mul_f32_e32 v47, v47, v163
	v_mul_f32_e32 v16, v16, v164
	v_mul_f32_e32 v17, v17, v164
	v_mul_f32_e32 v18, v18, v164
	v_mul_f32_e32 v19, v19, v164
	v_mul_f32_e32 v20, v20, v164
	v_mul_f32_e32 v21, v21, v164
	v_mul_f32_e32 v22, v22, v164
	v_mul_f32_e32 v23, v23, v164
	v_mul_f32_e32 v24, v24, v164
	v_mul_f32_e32 v25, v25, v164
	v_mul_f32_e32 v26, v26, v164
	v_mul_f32_e32 v27, v27, v164
	v_mul_f32_e32 v28, v28, v164
	v_mul_f32_e32 v29, v29, v164
	v_mul_f32_e32 v30, v30, v164
	v_mul_f32_e32 v31, v31, v164
	v_mul_f32_e32 v0, v0, v165
	v_mul_f32_e32 v1, v1, v165
	v_mul_f32_e32 v2, v2, v165
	v_mul_f32_e32 v3, v3, v165
	v_mul_f32_e32 v4, v4, v165
	v_mul_f32_e32 v5, v5, v165
	v_mul_f32_e32 v6, v6, v165
	v_mul_f32_e32 v7, v7, v165
	v_mul_f32_e32 v8, v8, v165
	v_mul_f32_e32 v9, v9, v165
	v_mul_f32_e32 v10, v10, v165
	v_mul_f32_e32 v11, v11, v165
	v_mul_f32_e32 v12, v12, v165
	v_mul_f32_e32 v13, v13, v165
	v_mul_f32_e32 v14, v14, v165
	v_mul_f32_e32 v15, v15, v165
	s_cmpk_ge_u32 s7, 32
	s_cbranch_scc1 .Lepi7_sample
; __device__ __forceinline__ unsigned cvt_pk_bf16(float lo, float hi) { unsigned r; asm volatile("v_cvt_pk_bf16_f32 %0, %1, %2" : "=v"(r) : "v"(lo), "v"(hi)); return r; }
; #define ST8(ptr, src) do { *(f32x4*)(ptr) = (f32x4){src[0], src[1], src[2], src[3]}; *(f32x4*)((ptr) + 4) = (f32x4){src[4], src[5], src[6], src[7]}; } while (0)
;     __device__ __forceinline__ void operator()(const f32x4 (&acc)[2][2][4][2], const Unit& u, int wr, int wc, int fr, int fq) const {
;     ...
;             for (int m = 0; m < 4; ++m) { bf16_t* rowp = O + (size_t)(row0 + ai * HALF + m * 16) * ldc + col0;
; #pragma unroll
;                 for (int bj = 0; bj < 2; ++bj) { const f32x4 v0 = acc[ai][bj][m][0] * rs[ai][m], v1 = acc[ai][bj][m][1] * rs[ai][m];
;                     u32x4 w; w.x = cvt_pk_bf16(v0[0], v0[1]); w.y = cvt_pk_bf16(v0[2], v0[3]); w.z = cvt_pk_bf16(v1[0], v1[1]); w.w = cvt_pk_bf16(v1[2], v1[3]);
;                     *(u32x4*)(rowp + bj * HALF) = w; } }
; template <int NT, bool SAMPLE>
; __device__ __forceinline__ void ffn_item(const bf16_t* U, int row0, bool has_hist, const float* st, int cgi, const float* w, const float* bias, bf16_t* ACT, float* state_out) {
;     ...
;     if (state_out) {
;     ...
;         ST8(state_out + 0 * FF2 + c0, g0); ST8(state_out + 1 * FF2 + c0, g1); ST8(state_out + 0 * FF2 + FF + c0, v0); ST8(state_out + 1 * FF2 + FF + c0, v1);
	v_cvt_pk_bf16_f32 v168, v124, v125
	v_cvt_pk_bf16_f32 v169, v126, v127
	v_cvt_pk_bf16_f32 v170, v120, v121
	v_cvt_pk_bf16_f32 v171, v122, v123
	v_cvt_pk_bf16_f32 v172, v116, v117
	v_cvt_pk_bf16_f32 v173, v118, v119
	v_cvt_pk_bf16_f32 v174, v112, v113
	v_cvt_pk_bf16_f32 v175, v114, v115
	s_mov_b32 exec_lo, 0x00030003
	s_mov_b32 exec_hi, 0x00030003
	global_store_dwordx4 v152, v[168:171], s[10:11]
	global_store_dwordx4 v152, v[172:175], s[12:13]
	s_mov_b64 exec, -1
	s_add_u32 s10, s10, 0x5600
	s_addc_u32 s11, s11, 0
	s_add_u32 s12, s12, 0x5600
	s_addc_u32 s13, s13, 0
	v_cvt_pk_bf16_f32 v168, v108, v109
	v_cvt_pk_bf16_f32 v169, v110, v111
	v_cvt_pk_bf16_f32 v170, v104, v105
	v_cvt_pk_bf16_f32 v171, v106, v107
	v_cvt_pk_bf16_f32 v172, v100, v101
	v_cvt_pk_bf16_f32 v173, v102, v103
	v_cvt_pk_bf16_f32 v174, v96, v97
	v_cvt_pk_bf16_f32 v175, v98, v99
	s_mov_b32 exec_lo, 0x00030003
	s_mov_b32 exec_hi, 0x00030003
	global_store_dwordx4 v152, v[168:171], s[10:11]
	global_store_dwordx4 v152, v[172:175], s[12:13]
	s_mov_b64 exec, -1
	s_add_u32 s10, s10, 0x5600
	s_addc_u32 s11, s11, 0
	s_add_u32 s12, s12, 0x5600
	s_addc_u32 s13, s13, 0
	v_cvt_pk_bf16_f32 v168, v92, v93
	v_cvt_pk_bf16_f32 v169, v94, v95
	v_cvt_pk_bf16_f32 v170, v88, v89
	v_cvt_pk_bf16_f32 v171, v90, v91
	v_cvt_pk_bf16_f32 v172, v84, v85
	v_cvt_pk_bf16_f32 v173, v86, v87
	v_cvt_pk_bf16_f32 v174, v80, v81
	v_cvt_pk_bf16_f32 v175, v82, v83
	s_mov_b32 exec_lo, 0x80038003
	s_mov_b32 exec_hi, 0x80038003
	global_store_dwordx4 v152, v[168:171], s[10:11]
	global_store_dwordx4 v152, v[172:175], s[12:13]
	s_mov_b64 exec, -1
	s_add_u32 s10, s10, 0x5600
	s_addc_u32 s11, s11, 0
	s_add_u32 s12, s12, 0x5600
	s_addc_u32 s13, s13, 0
	v_cvt_pk_bf16_f32 v168, v76, v77
	v_cvt_pk_bf16_f32 v169, v78, v79
	v_cvt_pk_bf16_f32 v170, v72, v73
	v_cvt_pk_bf16_f32 v171, v74, v75
	v_cvt_pk_bf16_f32 v172, v68, v69
	v_cvt_pk_bf16_f32 v173, v70, v71
	v_cvt_pk_bf16_f32 v174, v64, v65
	v_cvt_pk_bf16_f32 v175, v66, v67
	s_mov_b32 exec_lo, 0x80038003
	s_mov_b32 exec_hi, 0x80038003
	global_store_dwordx4 v152, v[168:171], s[10:11]
	global_store_dwordx4 v152, v[172:175], s[12:13]
	s_mov_b64 exec, -1
	s_add_u32 s10, s10, 0x29fe00
	s_addc_u32 s11, s11, 0
	s_add_u32 s12, s12, 0x29fe00
	s_addc_u32 s13, s13, 0
	v_cvt_pk_bf16_f32 v168, v60, v61
	v_cvt_pk_bf16_f32 v169, v62, v63
	v_cvt_pk_bf16_f32 v170, v56, v57
	v_cvt_pk_bf16_f32 v171, v58, v59
	v_cvt_pk_bf16_f32 v172, v52, v53
	v_cvt_pk_bf16_f32 v173, v54, v55
	v_cvt_pk_bf16_f32 v174, v48, v49
	v_cvt_pk_bf16_f32 v175, v50, v51
	s_mov_b32 exec_lo, 0x00030003
	s_mov_b32 exec_hi, 0x00030003
	global_store_dwordx4 v152, v[168:171], s[10:11]
	global_store_dwordx4 v152, v[172:175], s[12:13]
	s_mov_b64 exec, -1
	s_add_u32 s10, s10, 0x5600
	s_addc_u32 s11, s11, 0
	s_add_u32 s12, s12, 0x5600
	s_addc_u32 s13, s13, 0
	v_cvt_pk_bf16_f32 v168, v44, v45
	v_cvt_pk_bf16_f32 v169, v46, v47
	v_cvt_pk_bf16_f32 v170, v40, v41
	v_cvt_pk_bf16_f32 v171, v42, v43
	v_cvt_pk_bf16_f32 v172, v36, v37
	v_cvt_pk_bf16_f32 v173, v38, v39
	v_cvt_pk_bf16_f32 v174, v32, v33
	v_cvt_pk_bf16_f32 v175, v34, v35
	s_mov_b32 exec_lo, 0x00030003
	s_mov_b32 exec_hi, 0x00030003
	global_store_dwordx4 v152, v[168:171], s[10:11]
	global_store_dwordx4 v152, v[172:175], s[12:13]
	s_mov_b64 exec, -1
	s_add_u32 s10, s10, 0x5600
	s_addc_u32 s11, s11, 0
	s_add_u32 s12, s12, 0x5600
	s_addc_u32 s13, s13, 0
	v_cvt_pk_bf16_f32 v168, v28, v29
	v_cvt_pk_bf16_f32 v169, v30, v31
	v_cvt_pk_bf16_f32 v170, v24, v25
	v_cvt_pk_bf16_f32 v171, v26, v27
	v_cvt_pk_bf16_f32 v172, v20, v21
	v_cvt_pk_bf16_f32 v173, v22, v23
	v_cvt_pk_bf16_f32 v174, v16, v17
	v_cvt_pk_bf16_f32 v175, v18, v19
	s_mov_b32 exec_lo, 0x80038003
	s_mov_b32 exec_hi, 0x80038003
	global_store_dwordx4 v152, v[168:171], s[10:11]
	global_store_dwordx4 v152, v[172:175], s[12:13]
	s_mov_b64 exec, -1
	s_cmp_eq_u32 s60, 0
	s_cbranch_scc1 .Lepi7_nostate2
	v_lshlrev_b32_e32 v244, 16, v168
	v_and_b32_e32 v245, 0xffff0000, v168
	v_lshlrev_b32_e32 v246, 16, v169
	v_and_b32_e32 v247, 0xffff0000, v169
	v_lshlrev_b32_e32 v248, 16, v170
	v_and_b32_e32 v249, 0xffff0000, v170
	v_lshlrev_b32_e32 v250, 16, v171
	v_and_b32_e32 v251, 0xffff0000, v171
	v_lshlrev_b32_e32 v144, 16, v172
	v_and_b32_e32 v145, 0xffff0000, v172
	v_lshlrev_b32_e32 v137, 16, v173
	v_and_b32_e32 v166, 0xffff0000, v173
	v_lshlrev_b32_e32 v167, 16, v174
	v_and_b32_e32 v213, 0xffff0000, v174
	v_lshlrev_b32_e32 v214, 16, v175
	v_and_b32_e32 v215, 0xffff0000, v175
	s_mov_b32 exec_lo, 0x80008000
	s_mov_b32 exec_hi, 0x80008000
	v_mov_b32_e32 v168, v244
	v_mov_b32_e32 v169, v245
	v_mov_b32_e32 v170, v246
	v_mov_b32_e32 v171, v247
	global_store_dwordx4 v149, v[168:171], s[62:63] offset:0
	s_nop 1
	v_mov_b32_e32 v172, v248
	v_mov_b32_e32 v173, v249
	v_mov_b32_e32 v174, v250
	v_mov_b32_e32 v175, v251
	global_store_dwordx4 v149, v[172:175], s[62:63] offset:16
	s_nop 1
	v_mov_b32_e32 v168, v144
	v_mov_b32_e32 v169, v145
	v_mov_b32_e32 v170, v137
	v_mov_b32_e32 v171, v166
	global_store_dwordx4 v149, v[168:171], s[64:65] offset:0
	s_nop 1
	v_mov_b32_e32 v172, v167
	v_mov_b32_e32 v173, v213
	v_mov_b32_e32 v174, v214
	v_mov_b32_e32 v175, v215
	global_store_dwordx4 v149, v[172:175], s[64:65] offset:16
	s_nop 1
	s_mov_b64 exec, -1
; __device__ __forceinline__ float siluf_(float x) { return x * __builtin_amdgcn_rcpf(1.f + __expf(-x)); }
; template <int NT, bool SAMPLE>
; __device__ __forceinline__ void ffn_item(const bf16_t* U, int row0, bool has_hist, const float* st, int cgi, const float* w, const float* bias, bf16_t* ACT, float* state_out) {
;     ...
;     for (int t = 0; t < NT; ++t) {
;         float cg_[8], cv_[8], o[8];
;         unpack8(rg[t], cg_); unpack8(rv[t], cv_);
; #pragma unroll
;         for (int e = 0; e < 8; ++e) {
;             const float gg = g0[e] * wg[0][e] + g1[e] * wg[1][e] + cg_[e] * wg[2][e] + bg[e];
;             const float vv = v0[e] * wv[0][e] + v1[e] * wv[1][e] + cv_[e] * wv[2][e] + bvv[e];
;             o[e] = siluf_(gg) * vv; g0[e] = g1[e]; g1[e] = cg_[e]; v0[e] = v1[e]; v1[e] = cv_[e]; }
.Lepi7_nostate2:
	s_add_u32 s10, s10, 0x5600
	s_addc_u32 s11, s11, 0
	s_add_u32 s12, s12, 0x5600
	s_addc_u32 s13, s13, 0
	v_cvt_pk_bf16_f32 v168, v12, v13
	v_cvt_pk_bf16_f32 v169, v14, v15
	v_cvt_pk_bf16_f32 v170, v8, v9
	v_cvt_pk_bf16_f32 v171, v10, v11
	v_cvt_pk_bf16_f32 v172, v4, v5
	v_cvt_pk_bf16_f32 v173, v6, v7
	v_cvt_pk_bf16_f32 v174, v0, v1
	v_cvt_pk_bf16_f32 v175, v2, v3
	s_mov_b32 exec_lo, 0x80038003
	s_mov_b32 exec_hi, 0x80038003
	global_store_dwordx4 v152, v[168:171], s[10:11]
	global_store_dwordx4 v152, v[172:175], s[12:13]
	s_mov_b64 exec, -1
	s_cmp_eq_u32 s60, 0
	s_cbranch_scc1 .Lepi7_nostate3
	v_lshlrev_b32_e32 v244, 16, v168
	v_and_b32_e32 v245, 0xffff0000, v168
	v_lshlrev_b32_e32 v246, 16, v169
	v_and_b32_e32 v247, 0xffff0000, v169
	v_lshlrev_b32_e32 v248, 16, v170
	v_and_b32_e32 v249, 0xffff0000, v170
	v_lshlrev_b32_e32 v250, 16, v171
	v_and_b32_e32 v251, 0xffff0000, v171
	v_lshlrev_b32_e32 v144, 16, v172
	v_and_b32_e32 v145, 0xffff0000, v172
	v_lshlrev_b32_e32 v137, 16, v173
	v_and_b32_e32 v166, 0xffff0000, v173
	v_lshlrev_b32_e32 v167, 16, v174
	v_and_b32_e32 v213, 0xffff0000, v174
	v_lshlrev_b32_e32 v214, 16, v175
	v_and_b32_e32 v215, 0xffff0000, v175
	s_mov_b32 exec_lo, 0x80008000
	s_mov_b32 exec_hi, 0x80008000
	v_mov_b32_e32 v168, v244
	v_mov_b32_e32 v169, v245
	v_mov_b32_e32 v170, v246
	v_mov_b32_e32 v171, v247
	global_store_dwordx4 v149, v[168:171], s[66:67] offset:0
	s_nop 1
	v_mov_b32_e32 v172, v248
	v_mov_b32_e32 v173, v249
	v_mov_b32_e32 v174, v250
	v_mov_b32_e32 v175, v251
	global_store_dwordx4 v149, v[172:175], s[66:67] offset:16
	s_nop 1
	v_mov_b32_e32 v168, v144
	v_mov_b32_e32 v169, v145
	v_mov_b32_e32 v170, v137
	v_mov_b32_e32 v171, v166
	global_store_dwordx4 v149, v[168:171], s[68:69] offset:0
	s_nop 1
	v_mov_b32_e32 v172, v167
	v_mov_b32_e32 v173, v213
	v_mov_b32_e32 v174, v214
	v_mov_b32_e32 v175, v215
	global_store_dwordx4 v149, v[172:175], s[68:69] offset:16
	s_nop 1
	s_mov_b64 exec, -1
.Lepi7_nostate3:
	s_waitcnt vmcnt(0)
	v_mov_b32_dpp v244, v92 row_shr:1 row_mask:0xf bank_mask:0xf
	v_mov_b32_dpp v245, v76 row_shr:1 row_mask:0xf bank_mask:0xf
	v_mov_b32_dpp v246, v84 row_shr:1 row_mask:0xf bank_mask:0xf
	v_mov_b32_dpp v247, v68 row_shr:1 row_mask:0xf bank_mask:0xf
	v_fma_f32 v248, v124, v208, v228
	v_fma_f32 v144, v116, v220, v236
	v_fma_f32 v249, v108, v208, v228
	v_fma_f32 v145, v100, v220, v236
	v_fma_f32 v250, v92, v208, v228
	v_fma_f32 v137, v84, v220, v236
	v_fma_f32 v251, v76, v208, v228
	v_fma_f32 v166, v68, v220, v236
	v_fmac_f32_e32 v248, v245, v192
	v_fmac_f32_e32 v144, v247, v200
	v_fmac_f32_e32 v249, v124, v192
	v_fmac_f32_e32 v145, v116, v200
	v_fmac_f32_e32 v250, v108, v192
	v_fmac_f32_e32 v137, v100, v200
	v_fmac_f32_e32 v251, v92, v192
	v_fmac_f32_e32 v166, v84, v200
	v_fmac_f32_e32 v248, v244, v176
	v_fmac_f32_e32 v144, v246, v184
	v_fmac_f32_e32 v249, v245, v176
	v_fmac_f32_e32 v145, v247, v184
	v_fmac_f32_e32 v250, v124, v176
	v_fmac_f32_e32 v137, v116, v184
	v_fmac_f32_e32 v251, v108, v176
	v_fmac_f32_e32 v166, v100, v184
	v_mul_f32_e32 v167, 0xbfb8aa3b, v248
	v_mul_f32_e32 v213, 0xbfb8aa3b, v249
	v_mul_f32_e32 v214, 0xbfb8aa3b, v250
	v_mul_f32_e32 v215, 0xbfb8aa3b, v251
	v_exp_f32_e32 v167, v167
	v_exp_f32_e32 v213, v213
	v_exp_f32_e32 v214, v214
	v_exp_f32_e32 v215, v215
	v_add_f32_e32 v167, 1.0, v167
	v_add_f32_e32 v213, 1.0, v213
	v_add_f32_e32 v214, 1.0, v214
	v_add_f32_e32 v215, 1.0, v215
	v_rcp_f32_e32 v167, v167
	v_rcp_f32_e32 v213, v213
	v_rcp_f32_e32 v214, v214
	v_rcp_f32_e32 v215, v215
	v_mul_f32_e32 v248, v248, v144
	v_mul_f32_e32 v249, v249, v145
	v_mul_f32_e32 v250, v250, v137
	v_mul_f32_e32 v251, v251, v166
	v_mul_f32_e32 v124, v248, v167
	v_mul_f32_e32 v108, v249, v213
	v_mul_f32_e32 v92, v250, v214
	v_mul_f32_e32 v76, v251, v215
	v_mov_b32_dpp v244, v93 row_shr:1 row_mask:0xf bank_mask:0xf
	v_mov_b32_dpp v245, v77 row_shr:1 row_mask:0xf bank_mask:0xf
	v_mov_b32_dpp v246, v85 row_shr:1 row_mask:0xf bank_mask:0xf
	v_mov_b32_dpp v247, v69 row_shr:1 row_mask:0xf bank_mask:0xf
	v_fma_f32 v248, v125, v209, v229
	v_fma_f32 v144, v117, v221, v237
	v_fma_f32 v249, v109, v209, v229
	v_fma_f32 v145, v101, v221, v237
	v_fma_f32 v250, v93, v209, v229
	v_fma_f32 v137, v85, v221, v237
	v_fma_f32 v251, v77, v209, v229
	v_fma_f32 v166, v69, v221, v237
	v_fmac_f32_e32 v248, v245, v193
	v_fmac_f32_e32 v144, v247, v201
	v_fmac_f32_e32 v249, v125, v193
	v_fmac_f32_e32 v145, v117, v201
	v_fmac_f32_e32 v250, v109, v193
	v_fmac_f32_e32 v137, v101, v201
	v_fmac_f32_e32 v251, v93, v193
	v_fmac_f32_e32 v166, v85, v201
	v_fmac_f32_e32 v248, v244, v177
	v_fmac_f32_e32 v144, v246, v185
	v_fmac_f32_e32 v249, v245, v177
	v_fmac_f32_e32 v145, v247, v185
	v_fmac_f32_e32 v250, v125, v177
	v_fmac_f32_e32 v137, v117, v185
	v_fmac_f32_e32 v251, v109, v177
	v_fmac_f32_e32 v166, v101, v185
	v_mul_f32_e32 v167, 0xbfb8aa3b, v248
	v_mul_f32_e32 v213, 0xbfb8aa3b, v249
	v_mul_f32_e32 v214, 0xbfb8aa3b, v250
	v_mul_f32_e32 v215, 0xbfb8aa3b, v251
	v_exp_f32_e32 v167, v167
	v_exp_f32_e32 v213, v213
	v_exp_f32_e32 v214, v214
	v_exp_f32_e32 v215, v215
	v_add_f32_e32 v167, 1.0, v167
	v_add_f32_e32 v213, 1.0, v213
	v_add_f32_e32 v214, 1.0, v214
	v_add_f32_e32 v215, 1.0, v215
	v_rcp_f32_e32 v167, v167
	v_rcp_f32_e32 v213, v213
	v_rcp_f32_e32 v214, v214
	v_rcp_f32_e32 v215, v215
	v_mul_f32_e32 v248, v248, v144
	v_mul_f32_e32 v249, v249, v145
	v_mul_f32_e32 v250, v250, v137
	v_mul_f32_e32 v251, v251, v166
	v_mul_f32_e32 v125, v248, v167
	v_mul_f32_e32 v109, v249, v213
	v_mul_f32_e32 v93, v250, v214
	v_mul_f32_e32 v77, v251, v215
	v_mov_b32_dpp v244, v94 row_shr:1 row_mask:0xf bank_mask:0xf
; __device__ __forceinline__ float siluf_(float x) { return x * __builtin_amdgcn_rcpf(1.f + __expf(-x)); }
; template <int NT, bool SAMPLE>
; __device__ __forceinline__ void ffn_item(const bf16_t* U, int row0, bool has_hist, const float* st, int cgi, const float* w, const float* bias, bf16_t* ACT, float* state_out) {
;     ...
;     for (int t = 0; t < NT; ++t) {
;         float cg_[8], cv_[8], o[8];
;         unpack8(rg[t], cg_); unpack8(rv[t], cv_);
; #pragma unroll
;         for (int e = 0; e < 8; ++e) {
;             const float gg = g0[e] * wg[0][e] + g1[e] * wg[1][e] + cg_[e] * wg[2][e] + bg[e];
;             const float vv = v0[e] * wv[0][e] + v1[e] * wv[1][e] + cv_[e] * wv[2][e] + bvv[e];
;             o[e] = siluf_(gg) * vv; g0[e] = g1[e]; g1[e] = cg_[e]; v0[e] = v1[e]; v1[e] = cv_[e]; }
	v_mov_b32_dpp v245, v78 row_shr:1 row_mask:0xf bank_mask:0xf
	v_mov_b32_dpp v246, v86 row_shr:1 row_mask:0xf bank_mask:0xf
	v_mov_b32_dpp v247, v70 row_shr:1 row_mask:0xf bank_mask:0xf
	v_fma_f32 v248, v126, v210, v230
	v_fma_f32 v144, v118, v222, v238
	v_fma_f32 v249, v110, v210, v230
	v_fma_f32 v145, v102, v222, v238
	v_fma_f32 v250, v94, v210, v230
	v_fma_f32 v137, v86, v222, v238
	v_fma_f32 v251, v78, v210, v230
	v_fma_f32 v166, v70, v222, v238
	v_fmac_f32_e32 v248, v245, v194
	v_fmac_f32_e32 v144, v247, v202
	v_fmac_f32_e32 v249, v126, v194
	v_fmac_f32_e32 v145, v118, v202
	v_fmac_f32_e32 v250, v110, v194
	v_fmac_f32_e32 v137, v102, v202
	v_fmac_f32_e32 v251, v94, v194
	v_fmac_f32_e32 v166, v86, v202
	v_fmac_f32_e32 v248, v244, v178
	v_fmac_f32_e32 v144, v246, v186
	v_fmac_f32_e32 v249, v245, v178
	v_fmac_f32_e32 v145, v247, v186
	v_fmac_f32_e32 v250, v126, v178
	v_fmac_f32_e32 v137, v118, v186
	v_fmac_f32_e32 v251, v110, v178
	v_fmac_f32_e32 v166, v102, v186
	v_mul_f32_e32 v167, 0xbfb8aa3b, v248
	v_mul_f32_e32 v213, 0xbfb8aa3b, v249
	v_mul_f32_e32 v214, 0xbfb8aa3b, v250
	v_mul_f32_e32 v215, 0xbfb8aa3b, v251
	v_exp_f32_e32 v167, v167
	v_exp_f32_e32 v213, v213
	v_exp_f32_e32 v214, v214
	v_exp_f32_e32 v215, v215
	v_add_f32_e32 v167, 1.0, v167
	v_add_f32_e32 v213, 1.0, v213
	v_add_f32_e32 v214, 1.0, v214
	v_add_f32_e32 v215, 1.0, v215
	v_rcp_f32_e32 v167, v167
	v_rcp_f32_e32 v213, v213
	v_rcp_f32_e32 v214, v214
	v_rcp_f32_e32 v215, v215
	v_mul_f32_e32 v248, v248, v144
	v_mul_f32_e32 v249, v249, v145
	v_mul_f32_e32 v250, v250, v137
	v_mul_f32_e32 v251, v251, v166
	v_mul_f32_e32 v126, v248, v167
	v_mul_f32_e32 v110, v249, v213
	v_mul_f32_e32 v94, v250, v214
	v_mul_f32_e32 v78, v251, v215
	v_mov_b32_dpp v244, v95 row_shr:1 row_mask:0xf bank_mask:0xf
	v_mov_b32_dpp v245, v79 row_shr:1 row_mask:0xf bank_mask:0xf
	v_mov_b32_dpp v246, v87 row_shr:1 row_mask:0xf bank_mask:0xf
	v_mov_b32_dpp v247, v71 row_shr:1 row_mask:0xf bank_mask:0xf
	v_fma_f32 v248, v127, v211, v231
	v_fma_f32 v144, v119, v223, v239
	v_fma_f32 v249, v111, v211, v231
	v_fma_f32 v145, v103, v223, v239
	v_fma_f32 v250, v95, v211, v231
	v_fma_f32 v137, v87, v223, v239
	v_fma_f32 v251, v79, v211, v231
	v_fma_f32 v166, v71, v223, v239
	v_fmac_f32_e32 v248, v245, v195
	v_fmac_f32_e32 v144, v247, v203
	v_fmac_f32_e32 v249, v127, v195
	v_fmac_f32_e32 v145, v119, v203
	v_fmac_f32_e32 v250, v111, v195
	v_fmac_f32_e32 v137, v103, v203
	v_fmac_f32_e32 v251, v95, v195
	v_fmac_f32_e32 v166, v87, v203
	v_fmac_f32_e32 v248, v244, v179
	v_fmac_f32_e32 v144, v246, v187
	v_fmac_f32_e32 v249, v245, v179
	v_fmac_f32_e32 v145, v247, v187
	v_fmac_f32_e32 v250, v127, v179
	v_fmac_f32_e32 v137, v119, v187
	v_fmac_f32_e32 v251, v111, v179
	v_fmac_f32_e32 v166, v103, v187
	v_mul_f32_e32 v167, 0xbfb8aa3b, v248
	v_mul_f32_e32 v213, 0xbfb8aa3b, v249
	v_mul_f32_e32 v214, 0xbfb8aa3b, v250
	v_mul_f32_e32 v215, 0xbfb8aa3b, v251
	v_exp_f32_e32 v167, v167
	v_exp_f32_e32 v213, v213
	v_exp_f32_e32 v214, v214
	v_exp_f32_e32 v215, v215
	v_add_f32_e32 v167, 1.0, v167
	v_add_f32_e32 v213, 1.0, v213
	v_add_f32_e32 v214, 1.0, v214
	v_add_f32_e32 v215, 1.0, v215
	v_rcp_f32_e32 v167, v167
	v_rcp_f32_e32 v213, v213
	v_rcp_f32_e32 v214, v214
	v_rcp_f32_e32 v215, v215
	v_mul_f32_e32 v248, v248, v144
	v_mul_f32_e32 v249, v249, v145
	v_mul_f32_e32 v250, v250, v137
	v_mul_f32_e32 v251, v251, v166
	v_mul_f32_e32 v127, v248, v167
	v_mul_f32_e32 v111, v249, v213
	v_mul_f32_e32 v95, v250, v214
	v_mul_f32_e32 v79, v251, v215
	v_mov_b32_dpp v244, v88 row_shr:1 row_mask:0xf bank_mask:0xf
	v_mov_b32_dpp v245, v72 row_shr:1 row_mask:0xf bank_mask:0xf
	v_mov_b32_dpp v246, v80 row_shr:1 row_mask:0xf bank_mask:0xf
	v_mov_b32_dpp v247, v64 row_shr:1 row_mask:0xf bank_mask:0xf
	v_fma_f32 v248, v120, v216, v232
	v_fma_f32 v144, v112, v224, v240
	v_fma_f32 v249, v104, v216, v232
	v_fma_f32 v145, v96, v224, v240
	v_fma_f32 v250, v88, v216, v232
	v_fma_f32 v137, v80, v224, v240
	v_fma_f32 v251, v72, v216, v232
	v_fma_f32 v166, v64, v224, v240
	v_fmac_f32_e32 v248, v245, v196
	v_fmac_f32_e32 v144, v247, v204
	v_fmac_f32_e32 v249, v120, v196
	v_fmac_f32_e32 v145, v112, v204
	v_fmac_f32_e32 v250, v104, v196
	v_fmac_f32_e32 v137, v96, v204
	v_fmac_f32_e32 v251, v88, v196
	v_fmac_f32_e32 v166, v80, v204
	v_fmac_f32_e32 v248, v244, v180
	v_fmac_f32_e32 v144, v246, v188
	v_fmac_f32_e32 v249, v245, v180
	v_fmac_f32_e32 v145, v247, v188
	v_fmac_f32_e32 v250, v120, v180
	v_fmac_f32_e32 v137, v112, v188
	v_fmac_f32_e32 v251, v104, v180
	v_fmac_f32_e32 v166, v96, v188
	v_mul_f32_e32 v167, 0xbfb8aa3b, v248
	v_mul_f32_e32 v213, 0xbfb8aa3b, v249
	v_mul_f32_e32 v214, 0xbfb8aa3b, v250
	v_mul_f32_e32 v215, 0xbfb8aa3b, v251
	v_exp_f32_e32 v167, v167
	v_exp_f32_e32 v213, v213
	v_exp_f32_e32 v214, v214
	v_exp_f32_e32 v215, v215
	v_add_f32_e32 v167, 1.0, v167
	v_add_f32_e32 v213, 1.0, v213
	v_add_f32_e32 v214, 1.0, v214
	v_add_f32_e32 v215, 1.0, v215
	v_rcp_f32_e32 v167, v167
	v_rcp_f32_e32 v213, v213
	v_rcp_f32_e32 v214, v214
	v_rcp_f32_e32 v215, v215
	v_mul_f32_e32 v248, v248, v144
	v_mul_f32_e32 v249, v249, v145
	v_mul_f32_e32 v250, v250, v137
	v_mul_f32_e32 v251, v251, v166
	v_mul_f32_e32 v120, v248, v167
	v_mul_f32_e32 v104, v249, v213
	v_mul_f32_e32 v88, v250, v214
	v_mul_f32_e32 v72, v251, v215
	v_mov_b32_dpp v244, v89 row_shr:1 row_mask:0xf bank_mask:0xf
	v_mov_b32_dpp v245, v73 row_shr:1 row_mask:0xf bank_mask:0xf
	v_mov_b32_dpp v246, v81 row_shr:1 row_mask:0xf bank_mask:0xf
	v_mov_b32_dpp v247, v65 row_shr:1 row_mask:0xf bank_mask:0xf
	v_fma_f32 v248, v121, v217, v233
	v_fma_f32 v144, v113, v225, v241
	v_fma_f32 v249, v105, v217, v233
; __device__ __forceinline__ float siluf_(float x) { return x * __builtin_amdgcn_rcpf(1.f + __expf(-x)); }
; template <int NT, bool SAMPLE>
; __device__ __forceinline__ void ffn_item(const bf16_t* U, int row0, bool has_hist, const float* st, int cgi, const float* w, const float* bias, bf16_t* ACT, float* state_out) {
;     ...
;     for (int t = 0; t < NT; ++t) {
;         float cg_[8], cv_[8], o[8];
;         unpack8(rg[t], cg_); unpack8(rv[t], cv_);
; #pragma unroll
;         for (int e = 0; e < 8; ++e) {
;             const float gg = g0[e] * wg[0][e] + g1[e] * wg[1][e] + cg_[e] * wg[2][e] + bg[e];
;             const float vv = v0[e] * wv[0][e] + v1[e] * wv[1][e] + cv_[e] * wv[2][e] + bvv[e];
;             o[e] = siluf_(gg) * vv; g0[e] = g1[e]; g1[e] = cg_[e]; v0[e] = v1[e]; v1[e] = cv_[e]; }
	v_fma_f32 v145, v97, v225, v241
	v_fma_f32 v250, v89, v217, v233
	v_fma_f32 v137, v81, v225, v241
	v_fma_f32 v251, v73, v217, v233
	v_fma_f32 v166, v65, v225, v241
	v_fmac_f32_e32 v248, v245, v197
	v_fmac_f32_e32 v144, v247, v205
	v_fmac_f32_e32 v249, v121, v197
	v_fmac_f32_e32 v145, v113, v205
	v_fmac_f32_e32 v250, v105, v197
	v_fmac_f32_e32 v137, v97, v205
	v_fmac_f32_e32 v251, v89, v197
	v_fmac_f32_e32 v166, v81, v205
	v_fmac_f32_e32 v248, v244, v181
	v_fmac_f32_e32 v144, v246, v189
	v_fmac_f32_e32 v249, v245, v181
	v_fmac_f32_e32 v145, v247, v189
	v_fmac_f32_e32 v250, v121, v181
	v_fmac_f32_e32 v137, v113, v189
	v_fmac_f32_e32 v251, v105, v181
	v_fmac_f32_e32 v166, v97, v189
	v_mul_f32_e32 v167, 0xbfb8aa3b, v248
	v_mul_f32_e32 v213, 0xbfb8aa3b, v249
	v_mul_f32_e32 v214, 0xbfb8aa3b, v250
	v_mul_f32_e32 v215, 0xbfb8aa3b, v251
	v_exp_f32_e32 v167, v167
	v_exp_f32_e32 v213, v213
	v_exp_f32_e32 v214, v214
	v_exp_f32_e32 v215, v215
	v_add_f32_e32 v167, 1.0, v167
	v_add_f32_e32 v213, 1.0, v213
	v_add_f32_e32 v214, 1.0, v214
	v_add_f32_e32 v215, 1.0, v215
	v_rcp_f32_e32 v167, v167
	v_rcp_f32_e32 v213, v213
	v_rcp_f32_e32 v214, v214
	v_rcp_f32_e32 v215, v215
	v_mul_f32_e32 v248, v248, v144
	v_mul_f32_e32 v249, v249, v145
	v_mul_f32_e32 v250, v250, v137
	v_mul_f32_e32 v251, v251, v166
	v_mul_f32_e32 v121, v248, v167
	v_mul_f32_e32 v105, v249, v213
	v_mul_f32_e32 v89, v250, v214
	v_mul_f32_e32 v73, v251, v215
	v_mov_b32_dpp v244, v90 row_shr:1 row_mask:0xf bank_mask:0xf
	v_mov_b32_dpp v245, v74 row_shr:1 row_mask:0xf bank_mask:0xf
	v_mov_b32_dpp v246, v82 row_shr:1 row_mask:0xf bank_mask:0xf
	v_mov_b32_dpp v247, v66 row_shr:1 row_mask:0xf bank_mask:0xf
	v_fma_f32 v248, v122, v218, v234
	v_fma_f32 v144, v114, v226, v242
	v_fma_f32 v249, v106, v218, v234
	v_fma_f32 v145, v98, v226, v242
	v_fma_f32 v250, v90, v218, v234
	v_fma_f32 v137, v82, v226, v242
	v_fma_f32 v251, v74, v218, v234
	v_fma_f32 v166, v66, v226, v242
	v_fmac_f32_e32 v248, v245, v198
	v_fmac_f32_e32 v144, v247, v206
	v_fmac_f32_e32 v249, v122, v198
	v_fmac_f32_e32 v145, v114, v206
	v_fmac_f32_e32 v250, v106, v198
	v_fmac_f32_e32 v137, v98, v206
	v_fmac_f32_e32 v251, v90, v198
	v_fmac_f32_e32 v166, v82, v206
	v_fmac_f32_e32 v248, v244, v182
	v_fmac_f32_e32 v144, v246, v190
	v_fmac_f32_e32 v249, v245, v182
	v_fmac_f32_e32 v145, v247, v190
	v_fmac_f32_e32 v250, v122, v182
	v_fmac_f32_e32 v137, v114, v190
	v_fmac_f32_e32 v251, v106, v182
	v_fmac_f32_e32 v166, v98, v190
	v_mul_f32_e32 v167, 0xbfb8aa3b, v248
	v_mul_f32_e32 v213, 0xbfb8aa3b, v249
	v_mul_f32_e32 v214, 0xbfb8aa3b, v250
	v_mul_f32_e32 v215, 0xbfb8aa3b, v251
	v_exp_f32_e32 v167, v167
	v_exp_f32_e32 v213, v213
	v_exp_f32_e32 v214, v214
	v_exp_f32_e32 v215, v215
	v_add_f32_e32 v167, 1.0, v167
	v_add_f32_e32 v213, 1.0, v213
	v_add_f32_e32 v214, 1.0, v214
	v_add_f32_e32 v215, 1.0, v215
	v_rcp_f32_e32 v167, v167
	v_rcp_f32_e32 v213, v213
	v_rcp_f32_e32 v214, v214
	v_rcp_f32_e32 v215, v215
	v_mul_f32_e32 v248, v248, v144
	v_mul_f32_e32 v249, v249, v145
	v_mul_f32_e32 v250, v250, v137
	v_mul_f32_e32 v251, v251, v166
	v_mul_f32_e32 v122, v248, v167
	v_mul_f32_e32 v106, v249, v213
	v_mul_f32_e32 v90, v250, v214
	v_mul_f32_e32 v74, v251, v215
	v_mov_b32_dpp v244, v91 row_shr:1 row_mask:0xf bank_mask:0xf
	v_mov_b32_dpp v245, v75 row_shr:1 row_mask:0xf bank_mask:0xf
	v_mov_b32_dpp v246, v83 row_shr:1 row_mask:0xf bank_mask:0xf
	v_mov_b32_dpp v247, v67 row_shr:1 row_mask:0xf bank_mask:0xf
	v_fma_f32 v248, v123, v219, v235
	v_fma_f32 v144, v115, v227, v243
	v_fma_f32 v249, v107, v219, v235
	v_fma_f32 v145, v99, v227, v243
	v_fma_f32 v250, v91, v219, v235
	v_fma_f32 v137, v83, v227, v243
	v_fma_f32 v251, v75, v219, v235
	v_fma_f32 v166, v67, v227, v243
	v_fmac_f32_e32 v248, v245, v199
	v_fmac_f32_e32 v144, v247, v207
	v_fmac_f32_e32 v249, v123, v199
	v_fmac_f32_e32 v145, v115, v207
	v_fmac_f32_e32 v250, v107, v199
	v_fmac_f32_e32 v137, v99, v207
	v_fmac_f32_e32 v251, v91, v199
	v_fmac_f32_e32 v166, v83, v207
	v_fmac_f32_e32 v248, v244, v183
	v_fmac_f32_e32 v144, v246, v191
	v_fmac_f32_e32 v249, v245, v183
	v_fmac_f32_e32 v145, v247, v191
	v_fmac_f32_e32 v250, v123, v183
	v_fmac_f32_e32 v137, v115, v191
	v_fmac_f32_e32 v251, v107, v183
	v_fmac_f32_e32 v166, v99, v191
	v_mul_f32_e32 v167, 0xbfb8aa3b, v248
	v_mul_f32_e32 v213, 0xbfb8aa3b, v249
	v_mul_f32_e32 v214, 0xbfb8aa3b, v250
	v_mul_f32_e32 v215, 0xbfb8aa3b, v251
	v_exp_f32_e32 v167, v167
	v_exp_f32_e32 v213, v213
	v_exp_f32_e32 v214, v214
	v_exp_f32_e32 v215, v215
	v_add_f32_e32 v167, 1.0, v167
	v_add_f32_e32 v213, 1.0, v213
	v_add_f32_e32 v214, 1.0, v214
	v_add_f32_e32 v215, 1.0, v215
	v_rcp_f32_e32 v167, v167
	v_rcp_f32_e32 v213, v213
	v_rcp_f32_e32 v214, v214
	v_rcp_f32_e32 v215, v215
	v_mul_f32_e32 v248, v248, v144
	v_mul_f32_e32 v249, v249, v145
	v_mul_f32_e32 v250, v250, v137
	v_mul_f32_e32 v251, v251, v166
	v_mul_f32_e32 v123, v248, v167
	v_mul_f32_e32 v107, v249, v213
	v_mul_f32_e32 v91, v250, v214
	v_mul_f32_e32 v75, v251, v215
	v_mov_b32_dpp v244, v28 row_shr:1 row_mask:0xf bank_mask:0xf
	v_mov_b32_dpp v245, v12 row_shr:1 row_mask:0xf bank_mask:0xf
	v_mov_b32_dpp v246, v20 row_shr:1 row_mask:0xf bank_mask:0xf
	v_mov_b32_dpp v247, v4 row_shr:1 row_mask:0xf bank_mask:0xf
	v_fma_f32 v248, v60, v208, v228
	v_fma_f32 v144, v52, v220, v236
	v_fma_f32 v249, v44, v208, v228
	v_fma_f32 v145, v36, v220, v236
	v_fma_f32 v250, v28, v208, v228
	v_fma_f32 v137, v20, v220, v236
	v_fma_f32 v251, v12, v208, v228
	v_fma_f32 v166, v4, v220, v236
	v_fmac_f32_e32 v248, v245, v192
	v_fmac_f32_e32 v144, v247, v200
	v_fmac_f32_e32 v249, v60, v192
	v_fmac_f32_e32 v145, v52, v200
	v_fmac_f32_e32 v250, v44, v192
; __device__ __forceinline__ float siluf_(float x) { return x * __builtin_amdgcn_rcpf(1.f + __expf(-x)); }
; template <int NT, bool SAMPLE>
; __device__ __forceinline__ void ffn_item(const bf16_t* U, int row0, bool has_hist, const float* st, int cgi, const float* w, const float* bias, bf16_t* ACT, float* state_out) {
;     ...
;     for (int t = 0; t < NT; ++t) {
;         float cg_[8], cv_[8], o[8];
;         unpack8(rg[t], cg_); unpack8(rv[t], cv_);
; #pragma unroll
;         for (int e = 0; e < 8; ++e) {
;             const float gg = g0[e] * wg[0][e] + g1[e] * wg[1][e] + cg_[e] * wg[2][e] + bg[e];
;             const float vv = v0[e] * wv[0][e] + v1[e] * wv[1][e] + cv_[e] * wv[2][e] + bvv[e];
;             o[e] = siluf_(gg) * vv; g0[e] = g1[e]; g1[e] = cg_[e]; v0[e] = v1[e]; v1[e] = cv_[e]; }
	v_fmac_f32_e32 v137, v36, v200
	v_fmac_f32_e32 v251, v28, v192
	v_fmac_f32_e32 v166, v20, v200
	v_fmac_f32_e32 v248, v244, v176
	v_fmac_f32_e32 v144, v246, v184
	v_fmac_f32_e32 v249, v245, v176
	v_fmac_f32_e32 v145, v247, v184
	v_fmac_f32_e32 v250, v60, v176
	v_fmac_f32_e32 v137, v52, v184
	v_fmac_f32_e32 v251, v44, v176
	v_fmac_f32_e32 v166, v36, v184
	v_mul_f32_e32 v167, 0xbfb8aa3b, v248
	v_mul_f32_e32 v213, 0xbfb8aa3b, v249
	v_mul_f32_e32 v214, 0xbfb8aa3b, v250
	v_mul_f32_e32 v215, 0xbfb8aa3b, v251
	v_exp_f32_e32 v167, v167
	v_exp_f32_e32 v213, v213
	v_exp_f32_e32 v214, v214
	v_exp_f32_e32 v215, v215
	v_add_f32_e32 v167, 1.0, v167
	v_add_f32_e32 v213, 1.0, v213
	v_add_f32_e32 v214, 1.0, v214
	v_add_f32_e32 v215, 1.0, v215
	v_rcp_f32_e32 v167, v167
	v_rcp_f32_e32 v213, v213
	v_rcp_f32_e32 v214, v214
	v_rcp_f32_e32 v215, v215
	v_mul_f32_e32 v248, v248, v144
	v_mul_f32_e32 v249, v249, v145
	v_mul_f32_e32 v250, v250, v137
	v_mul_f32_e32 v251, v251, v166
	v_mul_f32_e32 v60, v248, v167
	v_mul_f32_e32 v44, v249, v213
	v_mul_f32_e32 v28, v250, v214
	v_mul_f32_e32 v12, v251, v215
	v_mov_b32_dpp v244, v29 row_shr:1 row_mask:0xf bank_mask:0xf
	v_mov_b32_dpp v245, v13 row_shr:1 row_mask:0xf bank_mask:0xf
	v_mov_b32_dpp v246, v21 row_shr:1 row_mask:0xf bank_mask:0xf
	v_mov_b32_dpp v247, v5 row_shr:1 row_mask:0xf bank_mask:0xf
	v_fma_f32 v248, v61, v209, v229
	v_fma_f32 v144, v53, v221, v237
	v_fma_f32 v249, v45, v209, v229
	v_fma_f32 v145, v37, v221, v237
	v_fma_f32 v250, v29, v209, v229
	v_fma_f32 v137, v21, v221, v237
	v_fma_f32 v251, v13, v209, v229
	v_fma_f32 v166, v5, v221, v237
	v_fmac_f32_e32 v248, v245, v193
	v_fmac_f32_e32 v144, v247, v201
	v_fmac_f32_e32 v249, v61, v193
	v_fmac_f32_e32 v145, v53, v201
	v_fmac_f32_e32 v250, v45, v193
	v_fmac_f32_e32 v137, v37, v201
	v_fmac_f32_e32 v251, v29, v193
	v_fmac_f32_e32 v166, v21, v201
	v_fmac_f32_e32 v248, v244, v177
	v_fmac_f32_e32 v144, v246, v185
	v_fmac_f32_e32 v249, v245, v177
	v_fmac_f32_e32 v145, v247, v185
	v_fmac_f32_e32 v250, v61, v177
	v_fmac_f32_e32 v137, v53, v185
	v_fmac_f32_e32 v251, v45, v177
	v_fmac_f32_e32 v166, v37, v185
	v_mul_f32_e32 v167, 0xbfb8aa3b, v248
	v_mul_f32_e32 v213, 0xbfb8aa3b, v249
	v_mul_f32_e32 v214, 0xbfb8aa3b, v250
	v_mul_f32_e32 v215, 0xbfb8aa3b, v251
	v_exp_f32_e32 v167, v167
	v_exp_f32_e32 v213, v213
	v_exp_f32_e32 v214, v214
	v_exp_f32_e32 v215, v215
	v_add_f32_e32 v167, 1.0, v167
	v_add_f32_e32 v213, 1.0, v213
	v_add_f32_e32 v214, 1.0, v214
	v_add_f32_e32 v215, 1.0, v215
	v_rcp_f32_e32 v167, v167
	v_rcp_f32_e32 v213, v213
	v_rcp_f32_e32 v214, v214
	v_rcp_f32_e32 v215, v215
	v_mul_f32_e32 v248, v248, v144
	v_mul_f32_e32 v249, v249, v145
	v_mul_f32_e32 v250, v250, v137
	v_mul_f32_e32 v251, v251, v166
	v_mul_f32_e32 v61, v248, v167
	v_mul_f32_e32 v45, v249, v213
	v_mul_f32_e32 v29, v250, v214
	v_mul_f32_e32 v13, v251, v215
	v_mov_b32_dpp v244, v30 row_shr:1 row_mask:0xf bank_mask:0xf
	v_mov_b32_dpp v245, v14 row_shr:1 row_mask:0xf bank_mask:0xf
	v_mov_b32_dpp v246, v22 row_shr:1 row_mask:0xf bank_mask:0xf
	v_mov_b32_dpp v247, v6 row_shr:1 row_mask:0xf bank_mask:0xf
	v_fma_f32 v248, v62, v210, v230
	v_fma_f32 v144, v54, v222, v238
	v_fma_f32 v249, v46, v210, v230
	v_fma_f32 v145, v38, v222, v238
	v_fma_f32 v250, v30, v210, v230
	v_fma_f32 v137, v22, v222, v238
	v_fma_f32 v251, v14, v210, v230
	v_fma_f32 v166, v6, v222, v238
	v_fmac_f32_e32 v248, v245, v194
	v_fmac_f32_e32 v144, v247, v202
	v_fmac_f32_e32 v249, v62, v194
	v_fmac_f32_e32 v145, v54, v202
	v_fmac_f32_e32 v250, v46, v194
	v_fmac_f32_e32 v137, v38, v202
	v_fmac_f32_e32 v251, v30, v194
	v_fmac_f32_e32 v166, v22, v202
	v_fmac_f32_e32 v248, v244, v178
	v_fmac_f32_e32 v144, v246, v186
	v_fmac_f32_e32 v249, v245, v178
	v_fmac_f32_e32 v145, v247, v186
	v_fmac_f32_e32 v250, v62, v178
	v_fmac_f32_e32 v137, v54, v186
	v_fmac_f32_e32 v251, v46, v178
	v_fmac_f32_e32 v166, v38, v186
	v_mul_f32_e32 v167, 0xbfb8aa3b, v248
	v_mul_f32_e32 v213, 0xbfb8aa3b, v249
	v_mul_f32_e32 v214, 0xbfb8aa3b, v250
	v_mul_f32_e32 v215, 0xbfb8aa3b, v251
	v_exp_f32_e32 v167, v167
	v_exp_f32_e32 v213, v213
	v_exp_f32_e32 v214, v214
	v_exp_f32_e32 v215, v215
	v_add_f32_e32 v167, 1.0, v167
	v_add_f32_e32 v213, 1.0, v213
	v_add_f32_e32 v214, 1.0, v214
	v_add_f32_e32 v215, 1.0, v215
	v_rcp_f32_e32 v167, v167
	v_rcp_f32_e32 v213, v213
	v_rcp_f32_e32 v214, v214
	v_rcp_f32_e32 v215, v215
	v_mul_f32_e32 v248, v248, v144
	v_mul_f32_e32 v249, v249, v145
	v_mul_f32_e32 v250, v250, v137
	v_mul_f32_e32 v251, v251, v166
	v_mul_f32_e32 v62, v248, v167
	v_mul_f32_e32 v46, v249, v213
	v_mul_f32_e32 v30, v250, v214
	v_mul_f32_e32 v14, v251, v215
	v_mov_b32_dpp v244, v31 row_shr:1 row_mask:0xf bank_mask:0xf
	v_mov_b32_dpp v245, v15 row_shr:1 row_mask:0xf bank_mask:0xf
	v_mov_b32_dpp v246, v23 row_shr:1 row_mask:0xf bank_mask:0xf
	v_mov_b32_dpp v247, v7 row_shr:1 row_mask:0xf bank_mask:0xf
	v_fma_f32 v248, v63, v211, v231
	v_fma_f32 v144, v55, v223, v239
	v_fma_f32 v249, v47, v211, v231
	v_fma_f32 v145, v39, v223, v239
	v_fma_f32 v250, v31, v211, v231
	v_fma_f32 v137, v23, v223, v239
	v_fma_f32 v251, v15, v211, v231
	v_fma_f32 v166, v7, v223, v239
	v_fmac_f32_e32 v248, v245, v195
	v_fmac_f32_e32 v144, v247, v203
	v_fmac_f32_e32 v249, v63, v195
	v_fmac_f32_e32 v145, v55, v203
	v_fmac_f32_e32 v250, v47, v195
	v_fmac_f32_e32 v137, v39, v203
	v_fmac_f32_e32 v251, v31, v195
	v_fmac_f32_e32 v166, v23, v203
	v_fmac_f32_e32 v248, v244, v179
	v_fmac_f32_e32 v144, v246, v187
	v_fmac_f32_e32 v249, v245, v179
	v_fmac_f32_e32 v145, v247, v187
	v_fmac_f32_e32 v250, v63, v179
	v_fmac_f32_e32 v137, v55, v187
	v_fmac_f32_e32 v251, v47, v179
	v_fmac_f32_e32 v166, v39, v187
; __device__ __forceinline__ float siluf_(float x) { return x * __builtin_amdgcn_rcpf(1.f + __expf(-x)); }
; template <int NT, bool SAMPLE>
; __device__ __forceinline__ void ffn_item(const bf16_t* U, int row0, bool has_hist, const float* st, int cgi, const float* w, const float* bias, bf16_t* ACT, float* state_out) {
;     ...
;     for (int t = 0; t < NT; ++t) {
;         float cg_[8], cv_[8], o[8];
;         unpack8(rg[t], cg_); unpack8(rv[t], cv_);
; #pragma unroll
;         for (int e = 0; e < 8; ++e) {
;             const float gg = g0[e] * wg[0][e] + g1[e] * wg[1][e] + cg_[e] * wg[2][e] + bg[e];
;             const float vv = v0[e] * wv[0][e] + v1[e] * wv[1][e] + cv_[e] * wv[2][e] + bvv[e];
;             o[e] = siluf_(gg) * vv; g0[e] = g1[e]; g1[e] = cg_[e]; v0[e] = v1[e]; v1[e] = cv_[e]; }
	v_mul_f32_e32 v167, 0xbfb8aa3b, v248
	v_mul_f32_e32 v213, 0xbfb8aa3b, v249
	v_mul_f32_e32 v214, 0xbfb8aa3b, v250
	v_mul_f32_e32 v215, 0xbfb8aa3b, v251
	v_exp_f32_e32 v167, v167
	v_exp_f32_e32 v213, v213
	v_exp_f32_e32 v214, v214
	v_exp_f32_e32 v215, v215
	v_add_f32_e32 v167, 1.0, v167
	v_add_f32_e32 v213, 1.0, v213
	v_add_f32_e32 v214, 1.0, v214
	v_add_f32_e32 v215, 1.0, v215
	v_rcp_f32_e32 v167, v167
	v_rcp_f32_e32 v213, v213
	v_rcp_f32_e32 v214, v214
	v_rcp_f32_e32 v215, v215
	v_mul_f32_e32 v248, v248, v144
	v_mul_f32_e32 v249, v249, v145
	v_mul_f32_e32 v250, v250, v137
	v_mul_f32_e32 v251, v251, v166
	v_mul_f32_e32 v63, v248, v167
	v_mul_f32_e32 v47, v249, v213
	v_mul_f32_e32 v31, v250, v214
	v_mul_f32_e32 v15, v251, v215
	v_mov_b32_dpp v244, v24 row_shr:1 row_mask:0xf bank_mask:0xf
	v_mov_b32_dpp v245, v8 row_shr:1 row_mask:0xf bank_mask:0xf
	v_mov_b32_dpp v246, v16 row_shr:1 row_mask:0xf bank_mask:0xf
	v_mov_b32_dpp v247, v0 row_shr:1 row_mask:0xf bank_mask:0xf
	v_fma_f32 v248, v56, v216, v232
	v_fma_f32 v144, v48, v224, v240
	v_fma_f32 v249, v40, v216, v232
	v_fma_f32 v145, v32, v224, v240
	v_fma_f32 v250, v24, v216, v232
	v_fma_f32 v137, v16, v224, v240
	v_fma_f32 v251, v8, v216, v232
	v_fma_f32 v166, v0, v224, v240
	v_fmac_f32_e32 v248, v245, v196
	v_fmac_f32_e32 v144, v247, v204
	v_fmac_f32_e32 v249, v56, v196
	v_fmac_f32_e32 v145, v48, v204
	v_fmac_f32_e32 v250, v40, v196
	v_fmac_f32_e32 v137, v32, v204
	v_fmac_f32_e32 v251, v24, v196
	v_fmac_f32_e32 v166, v16, v204
	v_fmac_f32_e32 v248, v244, v180
	v_fmac_f32_e32 v144, v246, v188
	v_fmac_f32_e32 v249, v245, v180
	v_fmac_f32_e32 v145, v247, v188
	v_fmac_f32_e32 v250, v56, v180
	v_fmac_f32_e32 v137, v48, v188
	v_fmac_f32_e32 v251, v40, v180
	v_fmac_f32_e32 v166, v32, v188
	v_mul_f32_e32 v167, 0xbfb8aa3b, v248
	v_mul_f32_e32 v213, 0xbfb8aa3b, v249
	v_mul_f32_e32 v214, 0xbfb8aa3b, v250
	v_mul_f32_e32 v215, 0xbfb8aa3b, v251
	v_exp_f32_e32 v167, v167
	v_exp_f32_e32 v213, v213
	v_exp_f32_e32 v214, v214
	v_exp_f32_e32 v215, v215
	v_add_f32_e32 v167, 1.0, v167
	v_add_f32_e32 v213, 1.0, v213
	v_add_f32_e32 v214, 1.0, v214
	v_add_f32_e32 v215, 1.0, v215
	v_rcp_f32_e32 v167, v167
	v_rcp_f32_e32 v213, v213
	v_rcp_f32_e32 v214, v214
	v_rcp_f32_e32 v215, v215
	v_mul_f32_e32 v248, v248, v144
	v_mul_f32_e32 v249, v249, v145
	v_mul_f32_e32 v250, v250, v137
	v_mul_f32_e32 v251, v251, v166
	v_mul_f32_e32 v56, v248, v167
	v_mul_f32_e32 v40, v249, v213
	v_mul_f32_e32 v24, v250, v214
	v_mul_f32_e32 v8, v251, v215
	v_mov_b32_dpp v244, v25 row_shr:1 row_mask:0xf bank_mask:0xf
	v_mov_b32_dpp v245, v9 row_shr:1 row_mask:0xf bank_mask:0xf
	v_mov_b32_dpp v246, v17 row_shr:1 row_mask:0xf bank_mask:0xf
	v_mov_b32_dpp v247, v1 row_shr:1 row_mask:0xf bank_mask:0xf
	v_fma_f32 v248, v57, v217, v233
	v_fma_f32 v144, v49, v225, v241
	v_fma_f32 v249, v41, v217, v233
	v_fma_f32 v145, v33, v225, v241
	v_fma_f32 v250, v25, v217, v233
	v_fma_f32 v137, v17, v225, v241
	v_fma_f32 v251, v9, v217, v233
	v_fma_f32 v166, v1, v225, v241
	v_fmac_f32_e32 v248, v245, v197
	v_fmac_f32_e32 v144, v247, v205
	v_fmac_f32_e32 v249, v57, v197
	v_fmac_f32_e32 v145, v49, v205
	v_fmac_f32_e32 v250, v41, v197
	v_fmac_f32_e32 v137, v33, v205
	v_fmac_f32_e32 v251, v25, v197
	v_fmac_f32_e32 v166, v17, v205
	v_fmac_f32_e32 v248, v244, v181
	v_fmac_f32_e32 v144, v246, v189
	v_fmac_f32_e32 v249, v245, v181
	v_fmac_f32_e32 v145, v247, v189
	v_fmac_f32_e32 v250, v57, v181
	v_fmac_f32_e32 v137, v49, v189
	v_fmac_f32_e32 v251, v41, v181
	v_fmac_f32_e32 v166, v33, v189
	v_mul_f32_e32 v167, 0xbfb8aa3b, v248
	v_mul_f32_e32 v213, 0xbfb8aa3b, v249
	v_mul_f32_e32 v214, 0xbfb8aa3b, v250
	v_mul_f32_e32 v215, 0xbfb8aa3b, v251
	v_exp_f32_e32 v167, v167
	v_exp_f32_e32 v213, v213
	v_exp_f32_e32 v214, v214
	v_exp_f32_e32 v215, v215
	v_add_f32_e32 v167, 1.0, v167
	v_add_f32_e32 v213, 1.0, v213
	v_add_f32_e32 v214, 1.0, v214
	v_add_f32_e32 v215, 1.0, v215
	v_rcp_f32_e32 v167, v167
	v_rcp_f32_e32 v213, v213
	v_rcp_f32_e32 v214, v214
	v_rcp_f32_e32 v215, v215
	v_mul_f32_e32 v248, v248, v144
	v_mul_f32_e32 v249, v249, v145
	v_mul_f32_e32 v250, v250, v137
	v_mul_f32_e32 v251, v251, v166
	v_mul_f32_e32 v57, v248, v167
	v_mul_f32_e32 v41, v249, v213
	v_mul_f32_e32 v25, v250, v214
	v_mul_f32_e32 v9, v251, v215
	v_mov_b32_dpp v244, v26 row_shr:1 row_mask:0xf bank_mask:0xf
	v_mov_b32_dpp v245, v10 row_shr:1 row_mask:0xf bank_mask:0xf
	v_mov_b32_dpp v246, v18 row_shr:1 row_mask:0xf bank_mask:0xf
	v_mov_b32_dpp v247, v2 row_shr:1 row_mask:0xf bank_mask:0xf
	v_fma_f32 v248, v58, v218, v234
	v_fma_f32 v144, v50, v226, v242
	v_fma_f32 v249, v42, v218, v234
	v_fma_f32 v145, v34, v226, v242
	v_fma_f32 v250, v26, v218, v234
	v_fma_f32 v137, v18, v226, v242
	v_fma_f32 v251, v10, v218, v234
	v_fma_f32 v166, v2, v226, v242
	v_fmac_f32_e32 v248, v245, v198
	v_fmac_f32_e32 v144, v247, v206
	v_fmac_f32_e32 v249, v58, v198
; __device__ __forceinline__ float siluf_(float x) { return x * __builtin_amdgcn_rcpf(1.f + __expf(-x)); }
; template <int NT, bool SAMPLE>
; __device__ __forceinline__ void ffn_item(const bf16_t* U, int row0, bool has_hist, const float* st, int cgi, const float* w, const float* bias, bf16_t* ACT, float* state_out) {
;     ...
;     for (int t = 0; t < NT; ++t) {
;         float cg_[8], cv_[8], o[8];
;         unpack8(rg[t], cg_); unpack8(rv[t], cv_);
; #pragma unroll
;         for (int e = 0; e < 8; ++e) {
;             const float gg = g0[e] * wg[0][e] + g1[e] * wg[1][e] + cg_[e] * wg[2][e] + bg[e];
;             const float vv = v0[e] * wv[0][e] + v1[e] * wv[1][e] + cv_[e] * wv[2][e] + bvv[e];
;             o[e] = siluf_(gg) * vv; g0[e] = g1[e]; g1[e] = cg_[e]; v0[e] = v1[e]; v1[e] = cv_[e]; }
;         *(u32x4*)(ACT + (size_t)(row0 + t) * FF + c0) = pack8(o);
	v_fmac_f32_e32 v145, v50, v206
	v_fmac_f32_e32 v250, v42, v198
	v_fmac_f32_e32 v137, v34, v206
	v_fmac_f32_e32 v251, v26, v198
	v_fmac_f32_e32 v166, v18, v206
	v_fmac_f32_e32 v248, v244, v182
	v_fmac_f32_e32 v144, v246, v190
	v_fmac_f32_e32 v249, v245, v182
	v_fmac_f32_e32 v145, v247, v190
	v_fmac_f32_e32 v250, v58, v182
	v_fmac_f32_e32 v137, v50, v190
	v_fmac_f32_e32 v251, v42, v182
	v_fmac_f32_e32 v166, v34, v190
	v_mul_f32_e32 v167, 0xbfb8aa3b, v248
	v_mul_f32_e32 v213, 0xbfb8aa3b, v249
	v_mul_f32_e32 v214, 0xbfb8aa3b, v250
	v_mul_f32_e32 v215, 0xbfb8aa3b, v251
	v_exp_f32_e32 v167, v167
	v_exp_f32_e32 v213, v213
	v_exp_f32_e32 v214, v214
	v_exp_f32_e32 v215, v215
	v_add_f32_e32 v167, 1.0, v167
	v_add_f32_e32 v213, 1.0, v213
	v_add_f32_e32 v214, 1.0, v214
	v_add_f32_e32 v215, 1.0, v215
	v_rcp_f32_e32 v167, v167
	v_rcp_f32_e32 v213, v213
	v_rcp_f32_e32 v214, v214
	v_rcp_f32_e32 v215, v215
	v_mul_f32_e32 v248, v248, v144
	v_mul_f32_e32 v249, v249, v145
	v_mul_f32_e32 v250, v250, v137
	v_mul_f32_e32 v251, v251, v166
	v_mul_f32_e32 v58, v248, v167
	v_mul_f32_e32 v42, v249, v213
	v_mul_f32_e32 v26, v250, v214
	v_mul_f32_e32 v10, v251, v215
	v_mov_b32_dpp v244, v27 row_shr:1 row_mask:0xf bank_mask:0xf
	v_mov_b32_dpp v245, v11 row_shr:1 row_mask:0xf bank_mask:0xf
	v_mov_b32_dpp v246, v19 row_shr:1 row_mask:0xf bank_mask:0xf
	v_mov_b32_dpp v247, v3 row_shr:1 row_mask:0xf bank_mask:0xf
	v_fma_f32 v248, v59, v219, v235
	v_fma_f32 v144, v51, v227, v243
	v_fma_f32 v249, v43, v219, v235
	v_fma_f32 v145, v35, v227, v243
	v_fma_f32 v250, v27, v219, v235
	v_fma_f32 v137, v19, v227, v243
	v_fma_f32 v251, v11, v219, v235
	v_fma_f32 v166, v3, v227, v243
	v_fmac_f32_e32 v248, v245, v199
	v_fmac_f32_e32 v144, v247, v207
	v_fmac_f32_e32 v249, v59, v199
	v_fmac_f32_e32 v145, v51, v207
	v_fmac_f32_e32 v250, v43, v199
	v_fmac_f32_e32 v137, v35, v207
	v_fmac_f32_e32 v251, v27, v199
	v_fmac_f32_e32 v166, v19, v207
	v_fmac_f32_e32 v248, v244, v183
	v_fmac_f32_e32 v144, v246, v191
	v_fmac_f32_e32 v249, v245, v183
	v_fmac_f32_e32 v145, v247, v191
	v_fmac_f32_e32 v250, v59, v183
	v_fmac_f32_e32 v137, v51, v191
	v_fmac_f32_e32 v251, v43, v183
	v_fmac_f32_e32 v166, v35, v191
	v_mul_f32_e32 v167, 0xbfb8aa3b, v248
	v_mul_f32_e32 v213, 0xbfb8aa3b, v249
	v_mul_f32_e32 v214, 0xbfb8aa3b, v250
	v_mul_f32_e32 v215, 0xbfb8aa3b, v251
	v_exp_f32_e32 v167, v167
	v_exp_f32_e32 v213, v213
	v_exp_f32_e32 v214, v214
	v_exp_f32_e32 v215, v215
	v_add_f32_e32 v167, 1.0, v167
	v_add_f32_e32 v213, 1.0, v213
	v_add_f32_e32 v214, 1.0, v214
	v_add_f32_e32 v215, 1.0, v215
	v_rcp_f32_e32 v167, v167
	v_rcp_f32_e32 v213, v213
	v_rcp_f32_e32 v214, v214
	v_rcp_f32_e32 v215, v215
	v_mul_f32_e32 v248, v248, v144
	v_mul_f32_e32 v249, v249, v145
	v_mul_f32_e32 v250, v250, v137
	v_mul_f32_e32 v251, v251, v166
	v_mul_f32_e32 v59, v248, v167
	v_mul_f32_e32 v43, v249, v213
	v_mul_f32_e32 v27, v250, v214
	v_mul_f32_e32 v11, v251, v215
	s_mov_b32 exec_lo, 0xfffcfffc
	s_mov_b32 exec_hi, 0xfffcfffc
	v_cvt_pk_bf16_f32 v168, v124, v125
	v_cvt_pk_bf16_f32 v169, v126, v127
	v_cvt_pk_bf16_f32 v170, v120, v121
	v_cvt_pk_bf16_f32 v171, v122, v123
	global_store_dwordx4 v136, v[168:171], s[14:15]
	s_add_u32 s14, s14, 0x2b00
	s_addc_u32 s15, s15, 0
	v_cvt_pk_bf16_f32 v172, v108, v109
	v_cvt_pk_bf16_f32 v173, v110, v111
	v_cvt_pk_bf16_f32 v174, v104, v105
	v_cvt_pk_bf16_f32 v175, v106, v107
	global_store_dwordx4 v136, v[172:175], s[14:15]
	s_add_u32 s14, s14, 0x2b00
	s_addc_u32 s15, s15, 0
	v_cvt_pk_bf16_f32 v168, v92, v93
	v_cvt_pk_bf16_f32 v169, v94, v95
	v_cvt_pk_bf16_f32 v170, v88, v89
	v_cvt_pk_bf16_f32 v171, v90, v91
	global_store_dwordx4 v136, v[168:171], s[14:15]
	s_add_u32 s14, s14, 0x2b00
	s_addc_u32 s15, s15, 0
	v_cvt_pk_bf16_f32 v172, v76, v77
	v_cvt_pk_bf16_f32 v173, v78, v79
	v_cvt_pk_bf16_f32 v174, v72, v73
	v_cvt_pk_bf16_f32 v175, v74, v75
	global_store_dwordx4 v136, v[172:175], s[14:15]
	s_add_u32 s14, s14, 0x14ff00
	s_addc_u32 s15, s15, 0
	v_cvt_pk_bf16_f32 v168, v60, v61
	v_cvt_pk_bf16_f32 v169, v62, v63
	v_cvt_pk_bf16_f32 v170, v56, v57
	v_cvt_pk_bf16_f32 v171, v58, v59
	global_store_dwordx4 v136, v[168:171], s[14:15]
	s_add_u32 s14, s14, 0x2b00
	s_addc_u32 s15, s15, 0
	v_cvt_pk_bf16_f32 v172, v44, v45
	v_cvt_pk_bf16_f32 v173, v46, v47
	v_cvt_pk_bf16_f32 v174, v40, v41
	v_cvt_pk_bf16_f32 v175, v42, v43
	global_store_dwordx4 v136, v[172:175], s[14:15]
	s_add_u32 s14, s14, 0x2b00
	s_addc_u32 s15, s15, 0
	v_cvt_pk_bf16_f32 v168, v28, v29
	v_cvt_pk_bf16_f32 v169, v30, v31
	v_cvt_pk_bf16_f32 v170, v24, v25
	v_cvt_pk_bf16_f32 v171, v26, v27
	global_store_dwordx4 v136, v[168:171], s[14:15]
	s_add_u32 s14, s14, 0x2b00
	s_addc_u32 s15, s15, 0
	v_cvt_pk_bf16_f32 v172, v12, v13
	v_cvt_pk_bf16_f32 v173, v14, v15
	v_cvt_pk_bf16_f32 v174, v8, v9
	v_cvt_pk_bf16_f32 v175, v10, v11
	global_store_dwordx4 v136, v[172:175], s[14:15]
	s_mov_b64 exec, -1
	s_branch .Lepi7_done
